# DSA softmax batched x4 + HGRN b_out_g half preloaded
# baseline (speedup 1.0000x reference)
.LBB0_166:
	v_lshlrev_b32_e32 v1, 5, v147
	v_lshlrev_b32_e32 v8, 4, v147
	v_lshrrev_b32_e32 v2, 4, v147
	v_lshrrev_b32_e32 v4, 2, v147
	v_and_b32_e32 v7, 0x60, v1
	v_and_b32_e32 v1, 0x1f0, v8
	v_and_b32_e32 v8, 0xf0, v8
	v_lshl_or_b32 v146, v2, 8, v8
	v_lshlrev_b32_e32 v8, 1, v4
	s_movk_i32 s3, 0x90
	v_lshrrev_b32_e32 v9, 7, v147
	v_mad_u32_u24 v148, v7, s3, v8
	v_and_b32_e32 v8, 0x7f, v147
	v_mul_u32_u24_e32 v12, 0x1100, v9
	v_bfe_u32 v6, v147, 5, 1
	v_or_b32_e32 v12, v12, v8
	v_lshlrev_b32_e32 v152, 1, v12
	v_mul_u32_u24_e32 v12, 0x88, v149
	v_lshlrev_b32_e32 v13, 4, v6
	v_lshlrev_b32_e32 v153, 3, v6
	v_lshl_add_u32 v154, v12, 1, v13
	v_lshlrev_b32_e32 v12, 2, v6
	v_mul_u32_u24_e32 v6, 0x830, v6
	v_lshlrev_b32_e32 v15, 2, v149
	v_sub_u32_e32 v12, v149, v12
	v_add3_u32 v156, v13, v6, v15
	v_lshlrev_b32_e32 v6, 2, v7
	s_movk_i32 s6, 0x210
	v_mad_u32_u24 v157, v4, s6, v6
	v_cmp_gt_i32_e64 s[38:39], 26, v12
	v_cmp_gt_i32_e64 s[6:7], 27, v12
	v_cmp_gt_i32_e64 s[36:37], 25, v12
	s_and_b64 s[38:39], s[6:7], s[38:39]
	v_cmp_gt_i32_e64 s[34:35], 24, v12
	s_and_b64 s[36:37], s[38:39], s[36:37]
	v_cmp_gt_i32_e64 s[28:29], 19, v12
	s_and_b64 s[34:35], s[36:37], s[34:35]
	v_cmp_gt_i32_e64 s[26:27], 18, v12
	s_and_b64 s[28:29], s[34:35], s[28:29]
	s_mov_b64 s[96:97], s[66:67]
	s_mov_b64 s[86:87], s[64:65]
	v_cmp_gt_i32_e64 s[24:25], 17, v12
	s_load_dwordx16 s[64:79], s[0:1], 0x40
	s_and_b64 s[26:27], s[28:29], s[26:27]
	v_mov_b32_e32 v127, 0
	v_cmp_gt_i32_e64 s[22:23], 16, v12
	s_and_b64 s[24:25], s[26:27], s[24:25]
	v_mov_b32_e32 v3, v127
	v_lshl_or_b32 v10, v9, 12, v8
	v_cmp_gt_i32_e64 s[20:21], 11, v12
	s_and_b64 s[22:23], s[24:25], s[22:23]
	v_lshlrev_b32_e32 v7, 1, v10
	v_cmp_gt_i32_e64 s[18:19], 10, v12
	v_lshlrev_b64 v[130:131], 10, v[2:3]
	v_and_b32_e32 v2, 15, v147
	s_and_b64 s[20:21], s[22:23], s[20:21]
	v_mov_b32_e32 v5, v127
	v_lshlrev_b32_e32 v159, 2, v10
	v_sub_u32_e32 v10, 0, v7
	v_cmp_gt_i32_e64 s[16:17], 9, v12
	v_mov_b32_e32 v7, v127
	v_lshl_or_b32 v130, v2, 4, v130
	v_lshlrev_b32_e32 v2, 6, v147
	s_and_b64 s[18:19], s[20:21], s[18:19]
	v_cmp_gt_i32_e64 s[14:15], 8, v12
	s_waitcnt lgkmcnt(0)
	v_lshl_add_u64 v[128:129], s[66:67], 0, v[6:7]
	global_load_dwordx4 v[236:239], v[128:129], off offset:64
	global_load_dwordx4 v[240:243], v[128:129], off offset:80
	global_load_dwordx4 v[244:247], v[128:129], off offset:96
	global_load_dwordx4 v[248:251], v[128:129], off offset:112
	s_waitcnt vmcnt(0)
	v_and_b32_e32 v6, 0xc0, v2
	v_lshlrev_b64 v[2:3], 11, v[4:5]
	s_and_b64 s[16:17], s[18:19], s[16:17]
	v_cmp_gt_i32_e64 s[12:13], 3, v12
	v_or_b32_e32 v2, v2, v6
	s_mov_b64 s[42:43], 0x6e40420
	s_and_b64 s[14:15], s[16:17], s[14:15]
	v_mov_b32_e32 v11, 0x11a00
	v_cmp_gt_i32_e64 s[10:11], 2, v12
	v_lshl_add_u64 v[136:137], v[2:3], 0, s[42:43]
	v_mbcnt_lo_u32_b32 v2, -1, 0
	s_and_b64 s[12:13], s[14:15], s[12:13]
	v_lshrrev_b32_e32 v126, 5, v147
	v_lshl_add_u32 v150, v147, 2, v11
	v_lshlrev_b32_e32 v11, 2, v8
	v_cmp_gt_i32_e64 s[8:9], 1, v12
	v_mbcnt_hi_u32_b32 v165, -1, v2
	s_and_b64 s[10:11], s[12:13], s[10:11]
	v_or_b32_e32 v151, 0x11a00, v11
	s_movk_i32 s4, 0x80
	v_mul_u32_u24_e32 v8, 0x90, v8
	v_lshlrev_b32_e32 v9, 6, v9
	v_sub_u32_e32 v14, 0, v153
	v_or_b32_e32 v158, 0x11800, v11
	v_cmp_gt_i32_e32 vcc, 0, v12
	v_mul_u32_u24_e32 v11, 0x90, v149
	v_lshlrev_b64 v[132:133], 11, v[126:127]
	v_lshlrev_b64 v[134:135], 10, v[4:5]
	v_and_b32_e32 v2, 64, v165
	s_and_b64 s[8:9], s[10:11], s[8:9]
	v_lshl_or_b32 v1, v126, 9, v1
	v_cmp_gt_u32_e64 s[4:5], s4, v147
	v_or_b32_e32 v155, 0x11800, v13
	v_lshl_or_b32 v132, v149, 4, v132
	v_or_b32_e32 v134, v134, v6
	v_mov_b32_e32 v126, 0x11ff0
	v_add_u32_e32 v160, v159, v10
	s_movk_i32 s33, 0x7fff
	v_add_u32_e32 v161, v8, v9
	s_mov_b32 s50, 0x7060302
	v_add_u32_e32 v162, v154, v14
	v_add_u32_e32 v163, v13, v11
	v_mov_b32_e32 v164, 0x358637bd
	s_mov_b64 s[62:63], 0x10000
	s_mov_b64 s[90:91], 0x20000
	v_xor_b32_e32 v166, 1, v165
	v_add_u32_e32 v167, 64, v2
	v_xor_b32_e32 v168, 2, v165
	s_and_b64 s[94:95], s[8:9], vcc
	v_mov_b32_e32 v169, 1
	s_branch .LBB0_169

.LBB0_175:
	s_or_b64 exec, exec, s[42:43]
	s_waitcnt lgkmcnt(0)
	v_cndmask_b32_e64 v195, v195, 0, s[4:5]
	v_add_f32_e32 v195, v96, v195
	v_max_f32_e32 v196, 0xc2a00000, v195
	v_mul_f32_e32 v197, 0x3fb8aa3b, v196
	v_mul_f32_e32 v96, 0x3fb8aa3b, v96
	v_exp_f32_e32 v197, v197
	v_exp_f32_e32 v96, v96
	v_mul_f32_e32 v196, 0xbfb8aa3b, v196
	v_exp_f32_e32 v196, v196
	v_lshlrev_b32_e32 v194, 16, v194
	v_sub_f32_e32 v96, 1.0, v96
	v_mul_f32_e32 v194, v197, v194
	v_mul_f32_e32 v96, v96, v196
	v_bfe_u32 v196, v194, 16, 1
	v_add3_u32 v194, v194, v196, s33
	ds_write_b16_d16_hi v152, v194
	v_bfe_u32 v194, v96, 16, 1
	v_add3_u32 v96, v96, v194, s33
	v_lshrrev_b32_e32 v96, 16, v96
	ds_write_b16 v152, v96 offset:17408
	ds_write_b16 v161, v96 offset:34816
	v_add_f32_e32 v96, v97, v195
	v_max_f32_e32 v194, 0xc2a00000, v96
	v_mul_f32_e32 v195, 0x3fb8aa3b, v194
	v_mul_f32_e32 v97, 0x3fb8aa3b, v97
	v_exp_f32_e32 v195, v195
	v_exp_f32_e32 v97, v97
	v_mul_f32_e32 v194, 0xbfb8aa3b, v194
	v_exp_f32_e32 v194, v194
	v_lshlrev_b32_e32 v193, 16, v193
	v_sub_f32_e32 v97, 1.0, v97
	v_mul_f32_e32 v193, v195, v193
	v_mul_f32_e32 v97, v97, v194
	v_bfe_u32 v194, v193, 16, 1
	v_add3_u32 v193, v193, v194, s33
	ds_write_b16_d16_hi v152, v193 offset:272
	v_bfe_u32 v193, v97, 16, 1
	v_add3_u32 v97, v97, v193, s33
	v_lshrrev_b32_e32 v97, 16, v97
	v_add_f32_e32 v96, v94, v96
	ds_write_b16 v152, v97 offset:17680
	ds_write_b16 v161, v97 offset:34818
	v_max_f32_e32 v97, 0xc2a00000, v96
	v_mul_f32_e32 v193, 0x3fb8aa3b, v97
	v_mul_f32_e32 v94, 0x3fb8aa3b, v94
	v_exp_f32_e32 v193, v193
	v_exp_f32_e32 v94, v94
	v_mul_f32_e32 v97, 0xbfb8aa3b, v97
	v_exp_f32_e32 v97, v97
	v_lshlrev_b32_e32 v192, 16, v192
	v_sub_f32_e32 v94, 1.0, v94
	v_mul_f32_e32 v192, v193, v192
	v_mul_f32_e32 v94, v94, v97
	v_bfe_u32 v97, v192, 16, 1
	v_add3_u32 v97, v192, v97, s33
	ds_write_b16_d16_hi v152, v97 offset:544
	v_bfe_u32 v97, v94, 16, 1
	v_add3_u32 v94, v94, v97, s33
	v_lshrrev_b32_e32 v94, 16, v94
	ds_write_b16 v152, v94 offset:17952
	ds_write_b16 v161, v94 offset:34820
	v_add_f32_e32 v94, v95, v96
	v_max_f32_e32 v96, 0xc2a00000, v94
	v_mul_f32_e32 v97, 0x3fb8aa3b, v96
	v_mul_f32_e32 v95, 0x3fb8aa3b, v95
	v_exp_f32_e32 v97, v97
	v_exp_f32_e32 v95, v95
	v_mul_f32_e32 v96, 0xbfb8aa3b, v96
	v_exp_f32_e32 v96, v96
	v_lshlrev_b32_e32 v191, 16, v191
	v_sub_f32_e32 v95, 1.0, v95
	v_mul_f32_e32 v97, v97, v191
	v_mul_f32_e32 v95, v95, v96
	v_bfe_u32 v96, v97, 16, 1
	v_add3_u32 v96, v97, v96, s33
	ds_write_b16_d16_hi v152, v96 offset:816
	v_bfe_u32 v96, v95, 16, 1
	v_add3_u32 v95, v95, v96, s33
	v_lshrrev_b32_e32 v95, 16, v95
	v_add_f32_e32 v94, v92, v94
	ds_write_b16 v152, v95 offset:18224
	ds_write_b16 v161, v95 offset:34822
	v_max_f32_e32 v95, 0xc2a00000, v94
	v_mul_f32_e32 v96, 0x3fb8aa3b, v95
	v_mul_f32_e32 v92, 0x3fb8aa3b, v92
	v_exp_f32_e32 v96, v96
	v_exp_f32_e32 v92, v92
	v_mul_f32_e32 v95, 0xbfb8aa3b, v95
	v_exp_f32_e32 v95, v95
	v_lshlrev_b32_e32 v97, 16, v190
	v_sub_f32_e32 v92, 1.0, v92
	v_mul_f32_e32 v96, v96, v97
	v_mul_f32_e32 v92, v92, v95
	v_bfe_u32 v95, v96, 16, 1
	v_add3_u32 v95, v96, v95, s33
	ds_write_b16_d16_hi v152, v95 offset:1088
	v_bfe_u32 v95, v92, 16, 1
	v_add3_u32 v92, v92, v95, s33
	v_lshrrev_b32_e32 v92, 16, v92
	ds_write_b16 v152, v92 offset:18496
	ds_write_b16 v161, v92 offset:34824
	v_add_f32_e32 v92, v93, v94
	v_max_f32_e32 v94, 0xc2a00000, v92
	v_mul_f32_e32 v95, 0x3fb8aa3b, v94
	v_mul_f32_e32 v93, 0x3fb8aa3b, v93
	v_exp_f32_e32 v95, v95
	v_exp_f32_e32 v93, v93
	v_mul_f32_e32 v94, 0xbfb8aa3b, v94
	v_exp_f32_e32 v94, v94
	v_lshlrev_b32_e32 v96, 16, v189
	v_sub_f32_e32 v93, 1.0, v93
	v_mul_f32_e32 v95, v95, v96
	v_mul_f32_e32 v93, v93, v94
	v_bfe_u32 v94, v95, 16, 1
	v_add3_u32 v94, v95, v94, s33
	ds_write_b16_d16_hi v152, v94 offset:1360
	v_bfe_u32 v94, v93, 16, 1
	v_add3_u32 v93, v93, v94, s33
	v_lshrrev_b32_e32 v93, 16, v93
	v_add_f32_e32 v92, v90, v92
	ds_write_b16 v152, v93 offset:18768
	ds_write_b16 v161, v93 offset:34826
	v_max_f32_e32 v93, 0xc2a00000, v92
	v_mul_f32_e32 v94, 0x3fb8aa3b, v93
	v_mul_f32_e32 v90, 0x3fb8aa3b, v90
	v_exp_f32_e32 v94, v94
	v_exp_f32_e32 v90, v90
	v_mul_f32_e32 v93, 0xbfb8aa3b, v93
	v_exp_f32_e32 v93, v93
	v_lshlrev_b32_e32 v95, 16, v188
	v_sub_f32_e32 v90, 1.0, v90
	v_mul_f32_e32 v94, v94, v95
	v_mul_f32_e32 v90, v90, v93
	v_bfe_u32 v93, v94, 16, 1
	v_add3_u32 v93, v94, v93, s33
	ds_write_b16_d16_hi v152, v93 offset:1632
	v_bfe_u32 v93, v90, 16, 1
	v_add3_u32 v90, v90, v93, s33
	v_lshrrev_b32_e32 v90, 16, v90
	ds_write_b16 v152, v90 offset:19040
	ds_write_b16 v161, v90 offset:34828
	v_add_f32_e32 v90, v91, v92
	v_max_f32_e32 v92, 0xc2a00000, v90
	v_mul_f32_e32 v93, 0x3fb8aa3b, v92
	v_mul_f32_e32 v91, 0x3fb8aa3b, v91
	v_exp_f32_e32 v93, v93
	v_exp_f32_e32 v91, v91
	v_mul_f32_e32 v92, 0xbfb8aa3b, v92
	v_exp_f32_e32 v92, v92
	v_lshlrev_b32_e32 v94, 16, v186
	v_sub_f32_e32 v91, 1.0, v91
	v_mul_f32_e32 v93, v93, v94
	v_mul_f32_e32 v91, v91, v92
	v_bfe_u32 v92, v93, 16, 1
	v_add3_u32 v92, v93, v92, s33
	ds_write_b16_d16_hi v152, v92 offset:1904
	v_bfe_u32 v92, v91, 16, 1
	v_add3_u32 v91, v91, v92, s33
	v_lshrrev_b32_e32 v91, 16, v91
	v_add_f32_e32 v90, v88, v90
	ds_write_b16 v152, v91 offset:19312
	ds_write_b16 v161, v91 offset:34830
	v_max_f32_e32 v91, 0xc2a00000, v90
	v_mul_f32_e32 v92, 0x3fb8aa3b, v91
	v_mul_f32_e32 v88, 0x3fb8aa3b, v88
	v_exp_f32_e32 v92, v92
	v_exp_f32_e32 v88, v88
	v_mul_f32_e32 v91, 0xbfb8aa3b, v91
	v_exp_f32_e32 v91, v91
	v_lshlrev_b32_e32 v93, 16, v187
	v_sub_f32_e32 v88, 1.0, v88
	v_mul_f32_e32 v92, v92, v93
	v_mul_f32_e32 v88, v88, v91
	v_bfe_u32 v91, v92, 16, 1
	v_add3_u32 v91, v92, v91, s33
	ds_write_b16_d16_hi v152, v91 offset:2176
	v_bfe_u32 v91, v88, 16, 1
	v_add3_u32 v88, v88, v91, s33
	v_lshrrev_b32_e32 v88, 16, v88
	ds_write_b16 v152, v88 offset:19584
	ds_write_b16 v161, v88 offset:34832
	v_add_f32_e32 v88, v89, v90
	v_max_f32_e32 v90, 0xc2a00000, v88
	v_mul_f32_e32 v91, 0x3fb8aa3b, v90
	v_mul_f32_e32 v89, 0x3fb8aa3b, v89
	v_exp_f32_e32 v91, v91
	v_exp_f32_e32 v89, v89
	v_mul_f32_e32 v90, 0xbfb8aa3b, v90
	v_exp_f32_e32 v90, v90
	v_lshlrev_b32_e32 v92, 16, v185
	v_sub_f32_e32 v89, 1.0, v89
	v_mul_f32_e32 v91, v91, v92
	v_mul_f32_e32 v89, v89, v90
	v_bfe_u32 v90, v91, 16, 1
	v_add3_u32 v90, v91, v90, s33
	ds_write_b16_d16_hi v152, v90 offset:2448
	v_bfe_u32 v90, v89, 16, 1
	v_add3_u32 v89, v89, v90, s33
	v_lshrrev_b32_e32 v89, 16, v89
	v_add_f32_e32 v88, v86, v88
	ds_write_b16 v152, v89 offset:19856
	ds_write_b16 v161, v89 offset:34834
	v_max_f32_e32 v89, 0xc2a00000, v88
	v_mul_f32_e32 v90, 0x3fb8aa3b, v89
	v_mul_f32_e32 v86, 0x3fb8aa3b, v86
	v_exp_f32_e32 v90, v90
	v_exp_f32_e32 v86, v86
	v_mul_f32_e32 v89, 0xbfb8aa3b, v89
	v_exp_f32_e32 v89, v89
	v_lshlrev_b32_e32 v91, 16, v184
	v_sub_f32_e32 v86, 1.0, v86
	v_mul_f32_e32 v90, v90, v91
	v_mul_f32_e32 v86, v86, v89
	v_bfe_u32 v89, v90, 16, 1
	v_add3_u32 v89, v90, v89, s33
	ds_write_b16_d16_hi v152, v89 offset:2720
	v_bfe_u32 v89, v86, 16, 1
	v_add3_u32 v86, v86, v89, s33
	v_lshrrev_b32_e32 v86, 16, v86
	ds_write_b16 v152, v86 offset:20128
	ds_write_b16 v161, v86 offset:34836
	v_add_f32_e32 v86, v87, v88
	v_max_f32_e32 v88, 0xc2a00000, v86
	v_mul_f32_e32 v89, 0x3fb8aa3b, v88
	v_mul_f32_e32 v87, 0x3fb8aa3b, v87
	v_exp_f32_e32 v89, v89
	v_exp_f32_e32 v87, v87
	v_mul_f32_e32 v88, 0xbfb8aa3b, v88
	v_exp_f32_e32 v88, v88
	v_lshlrev_b32_e32 v90, 16, v183
	v_sub_f32_e32 v87, 1.0, v87
	v_mul_f32_e32 v89, v89, v90
	v_mul_f32_e32 v87, v87, v88
	v_bfe_u32 v88, v89, 16, 1
	v_add3_u32 v88, v89, v88, s33
	ds_write_b16_d16_hi v152, v88 offset:2992
	v_bfe_u32 v88, v87, 16, 1
	v_add3_u32 v87, v87, v88, s33
	v_lshrrev_b32_e32 v87, 16, v87
	v_add_f32_e32 v86, v84, v86
	ds_write_b16 v152, v87 offset:20400
	ds_write_b16 v161, v87 offset:34838
	v_max_f32_e32 v87, 0xc2a00000, v86
	v_mul_f32_e32 v88, 0x3fb8aa3b, v87
	v_mul_f32_e32 v84, 0x3fb8aa3b, v84
	v_exp_f32_e32 v88, v88
	v_exp_f32_e32 v84, v84
	v_mul_f32_e32 v87, 0xbfb8aa3b, v87
	v_exp_f32_e32 v87, v87
	v_lshlrev_b32_e32 v89, 16, v182
	v_sub_f32_e32 v84, 1.0, v84
	v_mul_f32_e32 v88, v88, v89
	v_mul_f32_e32 v84, v84, v87
	v_bfe_u32 v87, v88, 16, 1
	v_add3_u32 v87, v88, v87, s33
	ds_write_b16_d16_hi v152, v87 offset:3264
	v_bfe_u32 v87, v84, 16, 1
	v_add3_u32 v84, v84, v87, s33
	v_lshrrev_b32_e32 v84, 16, v84
	ds_write_b16 v152, v84 offset:20672
	ds_write_b16 v161, v84 offset:34840
	v_add_f32_e32 v84, v85, v86
	v_max_f32_e32 v86, 0xc2a00000, v84
	v_mul_f32_e32 v87, 0x3fb8aa3b, v86
	v_mul_f32_e32 v85, 0x3fb8aa3b, v85
	v_exp_f32_e32 v87, v87
	v_exp_f32_e32 v85, v85
	v_mul_f32_e32 v86, 0xbfb8aa3b, v86
	v_exp_f32_e32 v86, v86
	v_lshlrev_b32_e32 v88, 16, v181
	v_sub_f32_e32 v85, 1.0, v85
	v_mul_f32_e32 v87, v87, v88
	v_mul_f32_e32 v85, v85, v86
	v_bfe_u32 v86, v87, 16, 1
	v_add3_u32 v86, v87, v86, s33
	ds_write_b16_d16_hi v152, v86 offset:3536
	v_bfe_u32 v86, v85, 16, 1
	v_add3_u32 v85, v85, v86, s33
	v_lshrrev_b32_e32 v85, 16, v85
	v_add_f32_e32 v84, v82, v84
	ds_write_b16 v152, v85 offset:20944
	ds_write_b16 v161, v85 offset:34842
	v_max_f32_e32 v85, 0xc2a00000, v84
	v_mul_f32_e32 v86, 0x3fb8aa3b, v85
	v_mul_f32_e32 v82, 0x3fb8aa3b, v82
	v_exp_f32_e32 v86, v86
	v_exp_f32_e32 v82, v82
	v_mul_f32_e32 v85, 0xbfb8aa3b, v85
	v_exp_f32_e32 v85, v85
	v_lshlrev_b32_e32 v87, 16, v180
	v_sub_f32_e32 v82, 1.0, v82
	v_mul_f32_e32 v86, v86, v87
	v_mul_f32_e32 v82, v82, v85
	v_bfe_u32 v85, v86, 16, 1
	v_add3_u32 v85, v86, v85, s33
	ds_write_b16_d16_hi v152, v85 offset:3808
	v_bfe_u32 v85, v82, 16, 1
	v_add3_u32 v82, v82, v85, s33
	v_lshrrev_b32_e32 v82, 16, v82
	ds_write_b16 v152, v82 offset:21216
	ds_write_b16 v161, v82 offset:34844
	v_add_f32_e32 v82, v83, v84
	v_max_f32_e32 v84, 0xc2a00000, v82
	v_mul_f32_e32 v85, 0x3fb8aa3b, v84
	v_mul_f32_e32 v83, 0x3fb8aa3b, v83
	v_exp_f32_e32 v85, v85
	v_exp_f32_e32 v83, v83
	v_mul_f32_e32 v84, 0xbfb8aa3b, v84
	v_exp_f32_e32 v84, v84
	v_lshlrev_b32_e32 v86, 16, v178
	v_sub_f32_e32 v83, 1.0, v83
	v_mul_f32_e32 v85, v85, v86
	v_mul_f32_e32 v83, v83, v84
	v_bfe_u32 v84, v85, 16, 1
	v_add3_u32 v84, v85, v84, s33
	ds_write_b16_d16_hi v152, v84 offset:4080
	v_bfe_u32 v84, v83, 16, 1
	v_add3_u32 v83, v83, v84, s33
	v_lshrrev_b32_e32 v83, 16, v83
	v_add_f32_e32 v82, v80, v82
	ds_write_b16 v152, v83 offset:21488
	ds_write_b16 v161, v83 offset:34846
	v_max_f32_e32 v83, 0xc2a00000, v82
	v_mul_f32_e32 v84, 0x3fb8aa3b, v83
	v_mul_f32_e32 v80, 0x3fb8aa3b, v80
	v_exp_f32_e32 v84, v84
	v_exp_f32_e32 v80, v80
	v_mul_f32_e32 v83, 0xbfb8aa3b, v83
	v_exp_f32_e32 v83, v83
	v_lshlrev_b32_e32 v85, 16, v179
	v_sub_f32_e32 v80, 1.0, v80
	v_mul_f32_e32 v84, v84, v85
	v_mul_f32_e32 v80, v80, v83
	v_bfe_u32 v83, v84, 16, 1
	v_add3_u32 v83, v84, v83, s33
	ds_write_b16_d16_hi v152, v83 offset:4352
	v_bfe_u32 v83, v80, 16, 1
	v_add3_u32 v80, v80, v83, s33
	v_lshrrev_b32_e32 v80, 16, v80
	ds_write_b16 v152, v80 offset:21760
	ds_write_b16 v161, v80 offset:34848
	v_add_f32_e32 v80, v81, v82
	v_max_f32_e32 v82, 0xc2a00000, v80
	v_mul_f32_e32 v83, 0x3fb8aa3b, v82
	v_mul_f32_e32 v81, 0x3fb8aa3b, v81
	v_exp_f32_e32 v83, v83
	v_exp_f32_e32 v81, v81
	v_mul_f32_e32 v82, 0xbfb8aa3b, v82
	v_exp_f32_e32 v82, v82
	v_lshlrev_b32_e32 v84, 16, v177
	v_sub_f32_e32 v81, 1.0, v81
	v_mul_f32_e32 v83, v83, v84
	v_mul_f32_e32 v81, v81, v82
	v_bfe_u32 v82, v83, 16, 1
	v_add3_u32 v82, v83, v82, s33
	ds_write_b16_d16_hi v152, v82 offset:4624
	v_bfe_u32 v82, v81, 16, 1
	v_add3_u32 v81, v81, v82, s33
	v_lshrrev_b32_e32 v81, 16, v81
	v_add_f32_e32 v80, v78, v80
	ds_write_b16 v152, v81 offset:22032
	ds_write_b16 v161, v81 offset:34850
	v_max_f32_e32 v81, 0xc2a00000, v80
	v_mul_f32_e32 v82, 0x3fb8aa3b, v81
	v_mul_f32_e32 v78, 0x3fb8aa3b, v78
	v_exp_f32_e32 v82, v82
	v_exp_f32_e32 v78, v78
	v_mul_f32_e32 v81, 0xbfb8aa3b, v81
	v_exp_f32_e32 v81, v81
	v_lshlrev_b32_e32 v83, 16, v176
	v_sub_f32_e32 v78, 1.0, v78
	v_mul_f32_e32 v82, v82, v83
	v_mul_f32_e32 v78, v78, v81
	v_bfe_u32 v81, v82, 16, 1
	v_add3_u32 v81, v82, v81, s33
	ds_write_b16_d16_hi v152, v81 offset:4896
	v_bfe_u32 v81, v78, 16, 1
	v_add3_u32 v78, v78, v81, s33
	v_lshrrev_b32_e32 v78, 16, v78
	ds_write_b16 v152, v78 offset:22304
	ds_write_b16 v161, v78 offset:34852
	v_add_f32_e32 v78, v79, v80
	v_max_f32_e32 v80, 0xc2a00000, v78
	v_mul_f32_e32 v81, 0x3fb8aa3b, v80
	v_mul_f32_e32 v79, 0x3fb8aa3b, v79
	v_exp_f32_e32 v81, v81
	v_exp_f32_e32 v79, v79
	v_mul_f32_e32 v80, 0xbfb8aa3b, v80
	v_exp_f32_e32 v80, v80
	v_lshlrev_b32_e32 v82, 16, v175
	v_sub_f32_e32 v79, 1.0, v79
	v_mul_f32_e32 v81, v81, v82
	v_mul_f32_e32 v79, v79, v80
	v_bfe_u32 v80, v81, 16, 1
	v_add3_u32 v80, v81, v80, s33
	ds_write_b16_d16_hi v152, v80 offset:5168
	v_bfe_u32 v80, v79, 16, 1
	v_add3_u32 v79, v79, v80, s33
	v_lshrrev_b32_e32 v79, 16, v79
	v_add_f32_e32 v78, v76, v78
	ds_write_b16 v152, v79 offset:22576
	ds_write_b16 v161, v79 offset:34854
	v_max_f32_e32 v79, 0xc2a00000, v78
	v_mul_f32_e32 v80, 0x3fb8aa3b, v79
	v_mul_f32_e32 v76, 0x3fb8aa3b, v76
	v_exp_f32_e32 v80, v80
	v_exp_f32_e32 v76, v76
	v_mul_f32_e32 v79, 0xbfb8aa3b, v79
	v_exp_f32_e32 v79, v79
	v_lshlrev_b32_e32 v81, 16, v125
	v_sub_f32_e32 v76, 1.0, v76
	v_mul_f32_e32 v80, v80, v81
	v_mul_f32_e32 v76, v76, v79
	v_bfe_u32 v79, v80, 16, 1
	v_add3_u32 v79, v80, v79, s33
	ds_write_b16_d16_hi v152, v79 offset:5440
	v_bfe_u32 v79, v76, 16, 1
	v_add3_u32 v76, v76, v79, s33
	v_lshrrev_b32_e32 v76, 16, v76
	ds_write_b16 v152, v76 offset:22848
	ds_write_b16 v161, v76 offset:34856
	v_add_f32_e32 v76, v77, v78
	v_max_f32_e32 v78, 0xc2a00000, v76
	v_mul_f32_e32 v79, 0x3fb8aa3b, v78
	v_mul_f32_e32 v77, 0x3fb8aa3b, v77
	v_exp_f32_e32 v79, v79
	v_exp_f32_e32 v77, v77
	v_mul_f32_e32 v78, 0xbfb8aa3b, v78
	v_exp_f32_e32 v78, v78
	v_lshlrev_b32_e32 v80, 16, v124
	v_sub_f32_e32 v77, 1.0, v77
	v_mul_f32_e32 v79, v79, v80
	v_mul_f32_e32 v77, v77, v78
	v_bfe_u32 v78, v79, 16, 1
	v_add3_u32 v78, v79, v78, s33
	ds_write_b16_d16_hi v152, v78 offset:5712
	v_bfe_u32 v78, v77, 16, 1
	v_add3_u32 v77, v77, v78, s33
	v_lshrrev_b32_e32 v77, 16, v77
	v_add_f32_e32 v76, v74, v76
	ds_write_b16 v152, v77 offset:23120
	ds_write_b16 v161, v77 offset:34858
	v_max_f32_e32 v77, 0xc2a00000, v76
	v_mul_f32_e32 v78, 0x3fb8aa3b, v77
	v_mul_f32_e32 v74, 0x3fb8aa3b, v74
	v_exp_f32_e32 v78, v78
	v_exp_f32_e32 v74, v74
	v_mul_f32_e32 v77, 0xbfb8aa3b, v77
	v_exp_f32_e32 v77, v77
	v_lshlrev_b32_e32 v79, 16, v123
	v_sub_f32_e32 v74, 1.0, v74
	v_mul_f32_e32 v78, v78, v79
	v_mul_f32_e32 v74, v74, v77
	v_bfe_u32 v77, v78, 16, 1
	v_add3_u32 v77, v78, v77, s33
	ds_write_b16_d16_hi v152, v77 offset:5984
	v_bfe_u32 v77, v74, 16, 1
	v_add3_u32 v74, v74, v77, s33
	v_lshrrev_b32_e32 v74, 16, v74
	ds_write_b16 v152, v74 offset:23392
	ds_write_b16 v161, v74 offset:34860
	v_add_f32_e32 v74, v75, v76
	v_max_f32_e32 v76, 0xc2a00000, v74
	v_mul_f32_e32 v77, 0x3fb8aa3b, v76
	v_mul_f32_e32 v75, 0x3fb8aa3b, v75
	v_exp_f32_e32 v77, v77
	v_exp_f32_e32 v75, v75
	v_mul_f32_e32 v76, 0xbfb8aa3b, v76
	v_exp_f32_e32 v76, v76
	v_lshlrev_b32_e32 v78, 16, v105
	v_sub_f32_e32 v75, 1.0, v75
	v_mul_f32_e32 v77, v77, v78
	v_mul_f32_e32 v75, v75, v76
	v_bfe_u32 v76, v77, 16, 1
	v_add3_u32 v76, v77, v76, s33
	ds_write_b16_d16_hi v152, v76 offset:6256
	v_bfe_u32 v76, v75, 16, 1
	v_add3_u32 v75, v75, v76, s33
	v_lshrrev_b32_e32 v75, 16, v75
	v_add_f32_e32 v74, v72, v74
	ds_write_b16 v152, v75 offset:23664
	ds_write_b16 v161, v75 offset:34862
	v_max_f32_e32 v75, 0xc2a00000, v74
	v_mul_f32_e32 v76, 0x3fb8aa3b, v75
	v_mul_f32_e32 v72, 0x3fb8aa3b, v72
	v_exp_f32_e32 v76, v76
	v_exp_f32_e32 v72, v72
	v_mul_f32_e32 v75, 0xbfb8aa3b, v75
	v_exp_f32_e32 v75, v75
	v_lshlrev_b32_e32 v77, 16, v122
	v_sub_f32_e32 v72, 1.0, v72
	v_mul_f32_e32 v76, v76, v77
	v_mul_f32_e32 v72, v72, v75
	v_bfe_u32 v75, v76, 16, 1
	v_add3_u32 v75, v76, v75, s33
	ds_write_b16_d16_hi v152, v75 offset:6528
	v_bfe_u32 v75, v72, 16, 1
	v_add3_u32 v72, v72, v75, s33
	v_lshrrev_b32_e32 v72, 16, v72
	ds_write_b16 v152, v72 offset:23936
	ds_write_b16 v161, v72 offset:34864
	v_add_f32_e32 v72, v73, v74
	v_max_f32_e32 v74, 0xc2a00000, v72
	v_mul_f32_e32 v75, 0x3fb8aa3b, v74
	v_mul_f32_e32 v73, 0x3fb8aa3b, v73
	v_exp_f32_e32 v75, v75
	v_exp_f32_e32 v73, v73
	v_mul_f32_e32 v74, 0xbfb8aa3b, v74
	v_exp_f32_e32 v74, v74
	v_lshlrev_b32_e32 v76, 16, v104
	v_sub_f32_e32 v73, 1.0, v73
	v_mul_f32_e32 v75, v75, v76
	v_mul_f32_e32 v73, v73, v74
	v_bfe_u32 v74, v75, 16, 1
	v_add3_u32 v74, v75, v74, s33
	ds_write_b16_d16_hi v152, v74 offset:6800
	v_bfe_u32 v74, v73, 16, 1
	v_add3_u32 v73, v73, v74, s33
	v_lshrrev_b32_e32 v73, 16, v73
	v_add_f32_e32 v72, v70, v72
	ds_write_b16 v152, v73 offset:24208
	ds_write_b16 v161, v73 offset:34866
	v_max_f32_e32 v73, 0xc2a00000, v72
	v_mul_f32_e32 v74, 0x3fb8aa3b, v73
	v_mul_f32_e32 v70, 0x3fb8aa3b, v70
	v_exp_f32_e32 v74, v74
	v_exp_f32_e32 v70, v70
	v_mul_f32_e32 v73, 0xbfb8aa3b, v73
	v_exp_f32_e32 v73, v73
	v_lshlrev_b32_e32 v75, 16, v103
	v_sub_f32_e32 v70, 1.0, v70
	v_mul_f32_e32 v74, v74, v75
	v_mul_f32_e32 v70, v70, v73
	v_bfe_u32 v73, v74, 16, 1
	v_add3_u32 v73, v74, v73, s33
	ds_write_b16_d16_hi v152, v73 offset:7072
	v_bfe_u32 v73, v70, 16, 1
	v_add3_u32 v70, v70, v73, s33
	v_lshrrev_b32_e32 v70, 16, v70
	ds_write_b16 v152, v70 offset:24480
	ds_write_b16 v161, v70 offset:34868
	v_add_f32_e32 v70, v71, v72
	v_max_f32_e32 v72, 0xc2a00000, v70
	v_mul_f32_e32 v73, 0x3fb8aa3b, v72
	v_mul_f32_e32 v71, 0x3fb8aa3b, v71
	v_exp_f32_e32 v73, v73
	v_exp_f32_e32 v71, v71
	v_mul_f32_e32 v72, 0xbfb8aa3b, v72
	v_exp_f32_e32 v72, v72
	v_lshlrev_b32_e32 v74, 16, v102
	v_sub_f32_e32 v71, 1.0, v71
	v_mul_f32_e32 v73, v73, v74
	v_mul_f32_e32 v71, v71, v72
	v_bfe_u32 v72, v73, 16, 1
	v_add3_u32 v72, v73, v72, s33
	ds_write_b16_d16_hi v152, v72 offset:7344
	v_bfe_u32 v72, v71, 16, 1
	v_add3_u32 v71, v71, v72, s33
	v_lshrrev_b32_e32 v71, 16, v71
	v_add_f32_e32 v70, v68, v70
	ds_write_b16 v152, v71 offset:24752
	ds_write_b16 v161, v71 offset:34870
	v_max_f32_e32 v71, 0xc2a00000, v70
	v_mul_f32_e32 v72, 0x3fb8aa3b, v71
	v_mul_f32_e32 v68, 0x3fb8aa3b, v68
	v_exp_f32_e32 v72, v72
	v_exp_f32_e32 v68, v68
	v_mul_f32_e32 v71, 0xbfb8aa3b, v71
	v_exp_f32_e32 v71, v71
	v_lshlrev_b32_e32 v73, 16, v101
	v_sub_f32_e32 v68, 1.0, v68
	v_mul_f32_e32 v72, v72, v73
	v_mul_f32_e32 v68, v68, v71
	v_bfe_u32 v71, v72, 16, 1
	v_add3_u32 v71, v72, v71, s33
	ds_write_b16_d16_hi v152, v71 offset:7616
	v_bfe_u32 v71, v68, 16, 1
	v_add3_u32 v68, v68, v71, s33
	v_lshrrev_b32_e32 v68, 16, v68
	ds_write_b16 v152, v68 offset:25024
	ds_write_b16 v161, v68 offset:34872
	v_add_f32_e32 v68, v69, v70
	v_max_f32_e32 v70, 0xc2a00000, v68
	v_mul_f32_e32 v71, 0x3fb8aa3b, v70
	v_mul_f32_e32 v69, 0x3fb8aa3b, v69
	v_exp_f32_e32 v71, v71
	v_exp_f32_e32 v69, v69
	v_mul_f32_e32 v70, 0xbfb8aa3b, v70
	v_exp_f32_e32 v70, v70
	v_lshlrev_b32_e32 v72, 16, v100
	v_sub_f32_e32 v69, 1.0, v69
	v_mul_f32_e32 v71, v71, v72
	v_mul_f32_e32 v69, v69, v70
	v_bfe_u32 v70, v71, 16, 1
	v_add3_u32 v70, v71, v70, s33
	ds_write_b16_d16_hi v152, v70 offset:7888
	v_bfe_u32 v70, v69, 16, 1
	v_add3_u32 v69, v69, v70, s33
	v_lshrrev_b32_e32 v69, 16, v69
	v_add_f32_e32 v68, v66, v68
	ds_write_b16 v152, v69 offset:25296
	ds_write_b16 v161, v69 offset:34874
	v_max_f32_e32 v69, 0xc2a00000, v68
	v_mul_f32_e32 v70, 0x3fb8aa3b, v69
	v_mul_f32_e32 v66, 0x3fb8aa3b, v66
	v_exp_f32_e32 v70, v70
	v_exp_f32_e32 v66, v66
	v_mul_f32_e32 v69, 0xbfb8aa3b, v69
	v_exp_f32_e32 v69, v69
	v_lshlrev_b32_e32 v71, 16, v99
	v_sub_f32_e32 v66, 1.0, v66
	v_mul_f32_e32 v70, v70, v71
	v_mul_f32_e32 v66, v66, v69
	v_bfe_u32 v69, v70, 16, 1
	v_add3_u32 v69, v70, v69, s33
	ds_write_b16_d16_hi v152, v69 offset:8160
	v_bfe_u32 v69, v66, 16, 1
	v_add3_u32 v66, v66, v69, s33
	v_lshrrev_b32_e32 v66, 16, v66
	ds_write_b16 v152, v66 offset:25568
	ds_write_b16 v161, v66 offset:34876
	v_add_f32_e32 v66, v67, v68
	v_max_f32_e32 v66, 0xc2a00000, v66
	v_mul_f32_e32 v68, 0x3fb8aa3b, v66
	v_mul_f32_e32 v67, 0x3fb8aa3b, v67
	v_exp_f32_e32 v68, v68
	v_exp_f32_e32 v67, v67
	v_mul_f32_e32 v66, 0xbfb8aa3b, v66
	v_exp_f32_e32 v66, v66
	v_lshlrev_b32_e32 v69, 16, v98
	v_sub_f32_e32 v67, 1.0, v67
	v_mul_f32_e32 v68, v68, v69
	v_mul_f32_e32 v66, v67, v66
	v_bfe_u32 v67, v68, 16, 1
	v_add3_u32 v67, v68, v67, s33
	ds_write_b16_d16_hi v152, v67 offset:8432
	v_bfe_u32 v67, v66, 16, 1
	v_add3_u32 v66, v66, v67, s33
	v_lshrrev_b32_e32 v66, 16, v66
	ds_write_b16 v152, v66 offset:25840
	ds_write_b16 v161, v66 offset:34878
	s_waitcnt lgkmcnt(0)
	s_barrier
	ds_read_b128 v[98:101], v154 offset:17408
	ds_read_b128 v[82:85], v154 offset:26112
	ds_read_b128 v[102:105], v154 offset:8704
	ds_read_b128 v[66:69], v154
	ds_read_b128 v[122:125], v154 offset:32
	ds_read_b128 v[176:179], v154 offset:17440
	ds_read_b128 v[180:183], v154 offset:26144
	ds_read_b128 v[184:187], v154 offset:8736
	s_waitcnt lgkmcnt(5)
	v_mfma_f32_32x32x16_bf16 v[82:97], v[82:85], v[102:105], 0
	s_waitcnt lgkmcnt(4)
	v_mfma_f32_32x32x16_bf16 v[66:81], v[98:101], v[66:69], 0
	s_waitcnt lgkmcnt(0)
	v_mfma_f32_32x32x16_bf16 v[82:97], v[180:183], v[184:187], v[82:97]
	v_mfma_f32_32x32x16_bf16 v[66:81], v[176:179], v[122:125], v[66:81]
	ds_read_b128 v[122:125], v154 offset:17472
	ds_read_b128 v[180:183], v154 offset:26176
	ds_read_b128 v[188:191], v154 offset:64
	ds_read_b128 v[192:195], v154 offset:8768
	s_waitcnt lgkmcnt(0)
	v_mfma_f32_32x32x16_bf16 v[82:97], v[180:183], v[192:195], v[82:97]
	v_mfma_f32_32x32x16_bf16 v[66:81], v[122:125], v[188:191], v[66:81]
	ds_read_b128 v[180:183], v154 offset:17504
	ds_read_b128 v[188:191], v154 offset:26208
	ds_read_b128 v[196:199], v154 offset:96
	ds_read_b128 v[200:203], v154 offset:8800
	s_waitcnt lgkmcnt(0)
	v_mfma_f32_32x32x16_bf16 v[82:97], v[188:191], v[200:203], v[82:97]
	v_mfma_f32_32x32x16_bf16 v[66:81], v[180:183], v[196:199], v[66:81]
	ds_read_b128 v[188:191], v154 offset:17536
	ds_read_b128 v[196:199], v154 offset:26240
	ds_read_b128 v[204:207], v154 offset:128
	ds_read_b128 v[208:211], v154 offset:8832
	s_waitcnt lgkmcnt(0)
	v_mfma_f32_32x32x16_bf16 v[82:97], v[196:199], v[208:211], v[82:97]
	v_mfma_f32_32x32x16_bf16 v[66:81], v[188:191], v[204:207], v[66:81]
	ds_read_b128 v[196:199], v154 offset:17568
	ds_read_b128 v[204:207], v154 offset:26272
	ds_read_b128 v[212:215], v154 offset:160
	ds_read_b128 v[216:219], v154 offset:8864
	s_waitcnt lgkmcnt(0)
	v_mfma_f32_32x32x16_bf16 v[82:97], v[204:207], v[216:219], v[82:97]
	v_mfma_f32_32x32x16_bf16 v[66:81], v[196:199], v[212:215], v[66:81]
	ds_read_b128 v[204:207], v154 offset:17600
	ds_read_b128 v[212:215], v154 offset:26304
	ds_read_b128 v[220:223], v154 offset:192
	ds_read_b128 v[224:227], v154 offset:8896
	s_waitcnt lgkmcnt(0)
	v_mfma_f32_32x32x16_bf16 v[82:97], v[212:215], v[224:227], v[82:97]
	v_mfma_f32_32x32x16_bf16 v[66:81], v[204:207], v[220:223], v[66:81]
	ds_read_b128 v[212:215], v154 offset:17632
	ds_read_b128 v[220:223], v154 offset:26336
	ds_read_b128 v[228:231], v154 offset:224
	ds_read_b128 v[232:235], v154 offset:8928
	s_waitcnt lgkmcnt(0)
	v_mfma_f32_32x32x16_bf16 v[82:97], v[220:223], v[232:235], v[82:97]
	v_mfma_f32_32x32x16_bf16 v[66:81], v[212:215], v[228:231], v[66:81]
	s_nop 10
	v_cndmask_b32_e64 v175, v96, 0, s[38:39]
	v_cndmask_b32_e64 v220, v97, 0, s[6:7]
	v_cndmask_b32_e64 v221, v94, 0, s[34:35]
	v_cndmask_b32_e64 v222, v95, 0, s[36:37]
	v_cndmask_b32_e64 v223, v92, 0, s[26:27]
	v_cndmask_b32_e64 v228, v93, 0, s[28:29]
	v_cndmask_b32_e64 v229, v90, 0, s[22:23]
	v_cndmask_b32_e64 v230, v91, 0, s[24:25]
	v_mfma_f32_32x32x16_bf16 v[90:105], v[98:101], v[102:105], 0
	v_cndmask_b32_e64 v88, v88, 0, s[18:19]
	v_cndmask_b32_e64 v89, v89, 0, s[20:21]
	v_cndmask_b32_e64 v86, v86, 0, s[14:15]
	v_cndmask_b32_e64 v87, v87, 0, s[16:17]
	v_cndmask_b32_e64 v84, v84, 0, s[10:11]
	v_cndmask_b32_e64 v85, v85, 0, s[12:13]
	v_cndmask_b32_e64 v82, v82, 0, s[94:95]
	v_mfma_f32_32x32x16_bf16 v[90:105], v[176:179], v[184:187], v[90:105]
	v_cndmask_b32_e64 v83, v83, 0, s[8:9]
	v_mfma_f32_32x32x16_bf16 v[90:105], v[122:125], v[192:195], v[90:105]
	v_mfma_f32_32x32x16_bf16 v[90:105], v[180:183], v[200:203], v[90:105]
	v_mfma_f32_32x32x16_bf16 v[90:105], v[188:191], v[208:211], v[90:105]
	v_mfma_f32_32x32x16_bf16 v[90:105], v[196:199], v[216:219], v[90:105]
	v_mfma_f32_32x32x16_bf16 v[90:105], v[204:207], v[224:227], v[90:105]
	v_mfma_f32_32x32x16_bf16 v[90:105], v[212:215], v[232:235], v[90:105]
	v_cndmask_b32_e64 v66, v66, 0, s[94:95]
	v_cndmask_b32_e64 v67, v67, 0, s[8:9]
	v_cndmask_b32_e64 v190, v74, 0, s[22:23]
	v_cndmask_b32_e64 v191, v75, 0, s[24:25]
	v_and_b32_sdwa v74, v67, v169 dst_sel:DWORD dst_unused:UNUSED_PAD src0_sel:WORD_1 src1_sel:DWORD
	v_and_b32_sdwa v75, v66, v169 dst_sel:DWORD dst_unused:UNUSED_PAD src0_sel:WORD_1 src1_sel:DWORD
	v_add3_u32 v66, v66, v75, s33
	v_add3_u32 v74, v67, v74, s33
	s_nop 3
	v_and_b32_sdwa v67, v91, v169 dst_sel:DWORD dst_unused:UNUSED_PAD src0_sel:WORD_1 src1_sel:DWORD
	v_and_b32_sdwa v75, v90, v169 dst_sel:DWORD dst_unused:UNUSED_PAD src0_sel:WORD_1 src1_sel:DWORD
	v_cndmask_b32_e64 v68, v68, 0, s[10:11]
	v_cndmask_b32_e64 v69, v69, 0, s[12:13]
	v_add3_u32 v90, v90, v75, s33
	v_add3_u32 v91, v91, v67, s33
	v_and_b32_sdwa v67, v83, v169 dst_sel:DWORD dst_unused:UNUSED_PAD src0_sel:WORD_1 src1_sel:DWORD
	v_and_b32_sdwa v75, v82, v169 dst_sel:DWORD dst_unused:UNUSED_PAD src0_sel:WORD_1 src1_sel:DWORD
	v_add3_u32 v180, v82, v75, s33
	v_add3_u32 v192, v83, v67, s33
	v_and_b32_sdwa v67, v69, v169 dst_sel:DWORD dst_unused:UNUSED_PAD src0_sel:WORD_1 src1_sel:DWORD
	v_and_b32_sdwa v75, v68, v169 dst_sel:DWORD dst_unused:UNUSED_PAD src0_sel:WORD_1 src1_sel:DWORD
	v_add3_u32 v75, v68, v75, s33
	v_add3_u32 v67, v69, v67, s33
	v_and_b32_sdwa v68, v93, v169 dst_sel:DWORD dst_unused:UNUSED_PAD src0_sel:WORD_1 src1_sel:DWORD
	v_and_b32_sdwa v69, v92, v169 dst_sel:DWORD dst_unused:UNUSED_PAD src0_sel:WORD_1 src1_sel:DWORD
	v_cndmask_b32_e64 v70, v70, 0, s[14:15]
	v_cndmask_b32_e64 v71, v71, 0, s[16:17]
	v_add3_u32 v92, v92, v69, s33
	v_add3_u32 v93, v93, v68, s33
	v_and_b32_sdwa v68, v85, v169 dst_sel:DWORD dst_unused:UNUSED_PAD src0_sel:WORD_1 src1_sel:DWORD
	v_and_b32_sdwa v69, v84, v169 dst_sel:DWORD dst_unused:UNUSED_PAD src0_sel:WORD_1 src1_sel:DWORD
	v_add3_u32 v181, v84, v69, s33
	v_add3_u32 v193, v85, v68, s33
	v_and_b32_sdwa v68, v71, v169 dst_sel:DWORD dst_unused:UNUSED_PAD src0_sel:WORD_1 src1_sel:DWORD
	v_and_b32_sdwa v69, v70, v169 dst_sel:DWORD dst_unused:UNUSED_PAD src0_sel:WORD_1 src1_sel:DWORD
	v_add3_u32 v70, v70, v69, s33
	v_add3_u32 v68, v71, v68, s33
	v_and_b32_sdwa v69, v95, v169 dst_sel:DWORD dst_unused:UNUSED_PAD src0_sel:WORD_1 src1_sel:DWORD
	v_and_b32_sdwa v71, v94, v169 dst_sel:DWORD dst_unused:UNUSED_PAD src0_sel:WORD_1 src1_sel:DWORD
	v_cndmask_b32_e64 v72, v72, 0, s[18:19]
	v_cndmask_b32_e64 v73, v73, 0, s[20:21]
	v_add3_u32 v94, v94, v71, s33
	v_add3_u32 v95, v95, v69, s33
	v_and_b32_sdwa v69, v87, v169 dst_sel:DWORD dst_unused:UNUSED_PAD src0_sel:WORD_1 src1_sel:DWORD
	v_and_b32_sdwa v71, v86, v169 dst_sel:DWORD dst_unused:UNUSED_PAD src0_sel:WORD_1 src1_sel:DWORD
	v_add3_u32 v182, v86, v71, s33
	v_add3_u32 v194, v87, v69, s33
	v_and_b32_sdwa v69, v73, v169 dst_sel:DWORD dst_unused:UNUSED_PAD src0_sel:WORD_1 src1_sel:DWORD
	v_and_b32_sdwa v71, v72, v169 dst_sel:DWORD dst_unused:UNUSED_PAD src0_sel:WORD_1 src1_sel:DWORD
	v_add3_u32 v71, v72, v71, s33
	v_add3_u32 v69, v73, v69, s33
	v_and_b32_sdwa v72, v97, v169 dst_sel:DWORD dst_unused:UNUSED_PAD src0_sel:WORD_1 src1_sel:DWORD
	v_and_b32_sdwa v73, v96, v169 dst_sel:DWORD dst_unused:UNUSED_PAD src0_sel:WORD_1 src1_sel:DWORD
	v_add3_u32 v86, v96, v73, s33
	v_add3_u32 v87, v97, v72, s33
	v_and_b32_sdwa v72, v89, v169 dst_sel:DWORD dst_unused:UNUSED_PAD src0_sel:WORD_1 src1_sel:DWORD
	v_and_b32_sdwa v73, v88, v169 dst_sel:DWORD dst_unused:UNUSED_PAD src0_sel:WORD_1 src1_sel:DWORD
	v_add3_u32 v183, v88, v73, s33
	v_add3_u32 v195, v89, v72, s33
	v_add_u32_e32 v196, 0xd000, v170
	v_perm_b32 v69, v69, v71, s50
	v_perm_b32 v68, v68, v70, s50
	v_perm_b32 v67, v67, v75, s50
	v_perm_b32 v66, v74, v66, s50
	v_perm_b32 v89, v87, v86, s50
	v_perm_b32 v88, v95, v94, s50
	v_perm_b32 v87, v93, v92, s50
	v_perm_b32 v86, v91, v90, s50
	ds_read2_b64 v[122:125], v196 offset0:8 offset1:10
	ds_read2_b64 v[82:85], v196 offset1:2
	ds_read2_b64 v[176:179], v196 offset0:4 offset1:6
	v_cndmask_b32_e64 v184, v80, 0, s[38:39]
	v_cndmask_b32_e64 v185, v81, 0, s[6:7]
	v_cndmask_b32_e64 v186, v78, 0, s[34:35]
	v_cndmask_b32_e64 v187, v79, 0, s[36:37]
	v_cndmask_b32_e64 v188, v76, 0, s[26:27]
	v_cndmask_b32_e64 v189, v77, 0, s[28:29]
	s_waitcnt lgkmcnt(1)
	v_mfma_f32_32x32x16_bf16 v[66:81], v[66:69], v[82:85], 0
	v_perm_b32 v183, v195, v183, s50
	v_perm_b32 v182, v194, v182, s50
	v_perm_b32 v181, v193, v181, s50
	v_perm_b32 v180, v192, v180, s50
	v_mfma_f32_32x32x16_bf16 v[82:97], v[86:89], v[82:85], 0
	s_nop 0
	v_mfma_f32_32x32x16_bf16 v[82:97], v[180:183], v[122:125], v[82:97]
	v_and_b32_sdwa v124, v99, v169 dst_sel:DWORD dst_unused:UNUSED_PAD src0_sel:WORD_1 src1_sel:DWORD
	v_and_b32_sdwa v125, v98, v169 dst_sel:DWORD dst_unused:UNUSED_PAD src0_sel:WORD_1 src1_sel:DWORD
	v_add3_u32 v125, v98, v125, s33
	v_add3_u32 v124, v99, v124, s33
	v_and_b32_sdwa v98, v230, v169 dst_sel:DWORD dst_unused:UNUSED_PAD src0_sel:WORD_1 src1_sel:DWORD
	v_and_b32_sdwa v99, v229, v169 dst_sel:DWORD dst_unused:UNUSED_PAD src0_sel:WORD_1 src1_sel:DWORD
	v_add3_u32 v180, v229, v99, s33
	v_add3_u32 v181, v230, v98, s33
	v_and_b32_sdwa v98, v189, v169 dst_sel:DWORD dst_unused:UNUSED_PAD src0_sel:WORD_1 src1_sel:DWORD
	v_and_b32_sdwa v99, v188, v169 dst_sel:DWORD dst_unused:UNUSED_PAD src0_sel:WORD_1 src1_sel:DWORD
	v_add3_u32 v182, v188, v99, s33
	v_add3_u32 v183, v189, v98, s33
	v_and_b32_sdwa v98, v101, v169 dst_sel:DWORD dst_unused:UNUSED_PAD src0_sel:WORD_1 src1_sel:DWORD
	v_and_b32_sdwa v99, v100, v169 dst_sel:DWORD dst_unused:UNUSED_PAD src0_sel:WORD_1 src1_sel:DWORD
	v_and_b32_sdwa v122, v191, v169 dst_sel:DWORD dst_unused:UNUSED_PAD src0_sel:WORD_1 src1_sel:DWORD
	v_and_b32_sdwa v123, v190, v169 dst_sel:DWORD dst_unused:UNUSED_PAD src0_sel:WORD_1 src1_sel:DWORD
	v_add3_u32 v188, v100, v99, s33
	v_add3_u32 v189, v101, v98, s33
	v_and_b32_sdwa v98, v228, v169 dst_sel:DWORD dst_unused:UNUSED_PAD src0_sel:WORD_1 src1_sel:DWORD
	v_and_b32_sdwa v99, v223, v169 dst_sel:DWORD dst_unused:UNUSED_PAD src0_sel:WORD_1 src1_sel:DWORD
	v_add3_u32 v123, v190, v123, s33
	v_add3_u32 v122, v191, v122, s33
	v_add3_u32 v190, v223, v99, s33
	v_add3_u32 v191, v228, v98, s33
	v_and_b32_sdwa v98, v187, v169 dst_sel:DWORD dst_unused:UNUSED_PAD src0_sel:WORD_1 src1_sel:DWORD
	v_and_b32_sdwa v99, v186, v169 dst_sel:DWORD dst_unused:UNUSED_PAD src0_sel:WORD_1 src1_sel:DWORD
	v_add3_u32 v186, v186, v99, s33
	v_add3_u32 v187, v187, v98, s33
	v_and_b32_sdwa v98, v103, v169 dst_sel:DWORD dst_unused:UNUSED_PAD src0_sel:WORD_1 src1_sel:DWORD
	v_and_b32_sdwa v99, v102, v169 dst_sel:DWORD dst_unused:UNUSED_PAD src0_sel:WORD_1 src1_sel:DWORD
	v_add3_u32 v192, v102, v99, s33
	v_add3_u32 v193, v103, v98, s33
	v_and_b32_sdwa v98, v222, v169 dst_sel:DWORD dst_unused:UNUSED_PAD src0_sel:WORD_1 src1_sel:DWORD
	v_and_b32_sdwa v99, v221, v169 dst_sel:DWORD dst_unused:UNUSED_PAD src0_sel:WORD_1 src1_sel:DWORD
	v_add3_u32 v194, v221, v99, s33
	v_add3_u32 v195, v222, v98, s33
	v_and_b32_sdwa v98, v185, v169 dst_sel:DWORD dst_unused:UNUSED_PAD src0_sel:WORD_1 src1_sel:DWORD
	v_and_b32_sdwa v99, v184, v169 dst_sel:DWORD dst_unused:UNUSED_PAD src0_sel:WORD_1 src1_sel:DWORD
	v_add3_u32 v102, v184, v99, s33
	v_add3_u32 v103, v185, v98, s33
	v_and_b32_sdwa v98, v105, v169 dst_sel:DWORD dst_unused:UNUSED_PAD src0_sel:WORD_1 src1_sel:DWORD
	v_and_b32_sdwa v99, v104, v169 dst_sel:DWORD dst_unused:UNUSED_PAD src0_sel:WORD_1 src1_sel:DWORD
	v_add3_u32 v184, v104, v99, s33
	v_add3_u32 v185, v105, v98, s33
	v_perm_b32 v105, v103, v102, s50
	v_perm_b32 v104, v187, v186, s50
	v_perm_b32 v103, v183, v182, s50
	v_perm_b32 v102, v122, v123, s50
	v_and_b32_sdwa v98, v220, v169 dst_sel:DWORD dst_unused:UNUSED_PAD src0_sel:WORD_1 src1_sel:DWORD
	v_and_b32_sdwa v99, v175, v169 dst_sel:DWORD dst_unused:UNUSED_PAD src0_sel:WORD_1 src1_sel:DWORD
	s_waitcnt lgkmcnt(0)
	v_mfma_f32_32x32x16_bf16 v[66:81], v[102:105], v[176:179], v[66:81]
	v_perm_b32 v105, v185, v184, s50
	v_perm_b32 v104, v193, v192, s50
	v_perm_b32 v103, v189, v188, s50
	v_perm_b32 v102, v124, v125, s50
	v_add3_u32 v175, v175, v99, s33
	v_add3_u32 v197, v220, v98, s33
	ds_read2_b64 v[98:101], v196 offset0:12 offset1:14
	v_mfma_f32_32x32x16_bf16 v[82:97], v[102:105], v[176:179], v[82:97]
	v_perm_b32 v105, v197, v175, s50
	v_perm_b32 v104, v195, v194, s50
	v_perm_b32 v103, v191, v190, s50
	v_perm_b32 v102, v181, v180, s50
	s_waitcnt lgkmcnt(0)
	s_nop 0
	v_mfma_f32_32x32x16_bf16 v[82:97], v[102:105], v[98:101], v[82:97]
	v_and_b32_sdwa v98, v3, v169 dst_sel:DWORD dst_unused:UNUSED_PAD src0_sel:WORD_1 src1_sel:DWORD
	v_and_b32_sdwa v99, v2, v169 dst_sel:DWORD dst_unused:UNUSED_PAD src0_sel:WORD_1 src1_sel:DWORD
	v_add3_u32 v102, v2, v99, s33
	v_add3_u32 v122, v3, v98, s33
	v_and_b32_sdwa v98, v5, v169 dst_sel:DWORD dst_unused:UNUSED_PAD src0_sel:WORD_1 src1_sel:DWORD
	v_and_b32_sdwa v99, v4, v169 dst_sel:DWORD dst_unused:UNUSED_PAD src0_sel:WORD_1 src1_sel:DWORD
	v_add3_u32 v103, v4, v99, s33
	v_add3_u32 v123, v5, v98, s33
	v_and_b32_sdwa v98, v7, v169 dst_sel:DWORD dst_unused:UNUSED_PAD src0_sel:WORD_1 src1_sel:DWORD
	v_and_b32_sdwa v99, v6, v169 dst_sel:DWORD dst_unused:UNUSED_PAD src0_sel:WORD_1 src1_sel:DWORD
	v_add3_u32 v104, v6, v99, s33
	v_add3_u32 v124, v7, v98, s33
	ds_read2_b64 v[98:101], v162 offset1:2
	v_and_b32_sdwa v105, v9, v169 dst_sel:DWORD dst_unused:UNUSED_PAD src0_sel:WORD_1 src1_sel:DWORD
	v_and_b32_sdwa v125, v8, v169 dst_sel:DWORD dst_unused:UNUSED_PAD src0_sel:WORD_1 src1_sel:DWORD
	v_add3_u32 v125, v8, v125, s33
	v_add3_u32 v105, v9, v105, s33
	v_add_u32_e32 v175, 0x2000, v162
	v_perm_b32 v105, v105, v125, s50
	v_perm_b32 v104, v124, v104, s50
	v_perm_b32 v103, v123, v103, s50
	v_perm_b32 v102, v122, v102, s50
	s_waitcnt lgkmcnt(0)
	s_nop 0
	v_mfma_f32_32x32x16_bf16 v[66:81], v[98:101], v[102:105], v[66:81]
	ds_read2_b64 v[98:101], v175 offset0:64 offset1:66
	ds_read2_b64 v[122:125], v162 offset0:4 offset1:6
	s_waitcnt lgkmcnt(1)
	v_mfma_f32_32x32x16_bf16 v[82:97], v[98:101], v[102:105], v[82:97]
	v_and_b32_sdwa v99, v10, v169 dst_sel:DWORD dst_unused:UNUSED_PAD src0_sel:WORD_1 src1_sel:DWORD
	v_and_b32_sdwa v100, v12, v169 dst_sel:DWORD dst_unused:UNUSED_PAD src0_sel:WORD_1 src1_sel:DWORD
	v_and_b32_sdwa v101, v14, v169 dst_sel:DWORD dst_unused:UNUSED_PAD src0_sel:WORD_1 src1_sel:DWORD
	v_and_b32_sdwa v98, v11, v169 dst_sel:DWORD dst_unused:UNUSED_PAD src0_sel:WORD_1 src1_sel:DWORD
	v_add3_u32 v102, v10, v99, s33
	v_and_b32_sdwa v99, v13, v169 dst_sel:DWORD dst_unused:UNUSED_PAD src0_sel:WORD_1 src1_sel:DWORD
	v_add3_u32 v103, v12, v100, s33
	v_and_b32_sdwa v100, v15, v169 dst_sel:DWORD dst_unused:UNUSED_PAD src0_sel:WORD_1 src1_sel:DWORD
	v_add3_u32 v104, v14, v101, s33
	v_and_b32_sdwa v101, v17, v169 dst_sel:DWORD dst_unused:UNUSED_PAD src0_sel:WORD_1 src1_sel:DWORD
	v_and_b32_sdwa v105, v16, v169 dst_sel:DWORD dst_unused:UNUSED_PAD src0_sel:WORD_1 src1_sel:DWORD
	v_add3_u32 v98, v11, v98, s33
	v_add3_u32 v99, v13, v99, s33
	v_add3_u32 v100, v15, v100, s33
	v_add3_u32 v105, v16, v105, s33
	v_add3_u32 v101, v17, v101, s33
	v_perm_b32 v101, v101, v105, s50
	v_perm_b32 v100, v100, v104, s50
	v_perm_b32 v99, v99, v103, s50
	v_perm_b32 v98, v98, v102, s50
	ds_read2_b64 v[102:105], v175 offset0:68 offset1:70
	s_waitcnt lgkmcnt(1)
	v_mfma_f32_32x32x16_bf16 v[66:81], v[122:125], v[98:101], v[66:81]
	s_waitcnt lgkmcnt(0)
	v_mfma_f32_32x32x16_bf16 v[82:97], v[102:105], v[98:101], v[82:97]
	v_and_b32_sdwa v98, v19, v169 dst_sel:DWORD dst_unused:UNUSED_PAD src0_sel:WORD_1 src1_sel:DWORD
	v_and_b32_sdwa v99, v18, v169 dst_sel:DWORD dst_unused:UNUSED_PAD src0_sel:WORD_1 src1_sel:DWORD
	v_add3_u32 v102, v18, v99, s33
	v_add3_u32 v122, v19, v98, s33
	v_and_b32_sdwa v98, v21, v169 dst_sel:DWORD dst_unused:UNUSED_PAD src0_sel:WORD_1 src1_sel:DWORD
	v_and_b32_sdwa v99, v20, v169 dst_sel:DWORD dst_unused:UNUSED_PAD src0_sel:WORD_1 src1_sel:DWORD
	v_add3_u32 v103, v20, v99, s33
	v_add3_u32 v123, v21, v98, s33
	v_and_b32_sdwa v98, v23, v169 dst_sel:DWORD dst_unused:UNUSED_PAD src0_sel:WORD_1 src1_sel:DWORD
	v_and_b32_sdwa v99, v22, v169 dst_sel:DWORD dst_unused:UNUSED_PAD src0_sel:WORD_1 src1_sel:DWORD
	v_add3_u32 v104, v22, v99, s33
	v_add3_u32 v124, v23, v98, s33
	ds_read2_b64 v[98:101], v162 offset0:8 offset1:10
	v_and_b32_sdwa v105, v25, v169 dst_sel:DWORD dst_unused:UNUSED_PAD src0_sel:WORD_1 src1_sel:DWORD
	v_and_b32_sdwa v125, v24, v169 dst_sel:DWORD dst_unused:UNUSED_PAD src0_sel:WORD_1 src1_sel:DWORD
	v_add3_u32 v125, v24, v125, s33
	v_add3_u32 v105, v25, v105, s33
	v_perm_b32 v105, v105, v125, s50
	v_perm_b32 v104, v124, v104, s50
	v_perm_b32 v103, v123, v103, s50
	v_perm_b32 v102, v122, v102, s50
	s_waitcnt lgkmcnt(0)
	s_nop 0
	v_mfma_f32_32x32x16_bf16 v[66:81], v[98:101], v[102:105], v[66:81]
	ds_read2_b64 v[98:101], v175 offset0:72 offset1:74
	ds_read2_b64 v[122:125], v162 offset0:12 offset1:14
	s_waitcnt lgkmcnt(1)
	v_mfma_f32_32x32x16_bf16 v[82:97], v[98:101], v[102:105], v[82:97]
	v_and_b32_sdwa v99, v26, v169 dst_sel:DWORD dst_unused:UNUSED_PAD src0_sel:WORD_1 src1_sel:DWORD
	v_and_b32_sdwa v100, v28, v169 dst_sel:DWORD dst_unused:UNUSED_PAD src0_sel:WORD_1 src1_sel:DWORD
	v_and_b32_sdwa v101, v30, v169 dst_sel:DWORD dst_unused:UNUSED_PAD src0_sel:WORD_1 src1_sel:DWORD
	v_and_b32_sdwa v98, v27, v169 dst_sel:DWORD dst_unused:UNUSED_PAD src0_sel:WORD_1 src1_sel:DWORD
	v_add3_u32 v102, v26, v99, s33
	v_and_b32_sdwa v99, v29, v169 dst_sel:DWORD dst_unused:UNUSED_PAD src0_sel:WORD_1 src1_sel:DWORD
	v_add3_u32 v103, v28, v100, s33
	v_and_b32_sdwa v100, v31, v169 dst_sel:DWORD dst_unused:UNUSED_PAD src0_sel:WORD_1 src1_sel:DWORD
	v_add3_u32 v104, v30, v101, s33
	v_and_b32_sdwa v101, v33, v169 dst_sel:DWORD dst_unused:UNUSED_PAD src0_sel:WORD_1 src1_sel:DWORD
	v_and_b32_sdwa v105, v32, v169 dst_sel:DWORD dst_unused:UNUSED_PAD src0_sel:WORD_1 src1_sel:DWORD
	v_add3_u32 v98, v27, v98, s33
	v_add3_u32 v99, v29, v99, s33
	v_add3_u32 v100, v31, v100, s33
	v_add3_u32 v105, v32, v105, s33
	v_add3_u32 v101, v33, v101, s33
	v_perm_b32 v101, v101, v105, s50
	v_perm_b32 v100, v100, v104, s50
	v_perm_b32 v99, v99, v103, s50
	v_perm_b32 v98, v98, v102, s50
	ds_read2_b64 v[102:105], v175 offset0:76 offset1:78
	s_waitcnt lgkmcnt(1)
	v_mfma_f32_32x32x16_bf16 v[66:81], v[122:125], v[98:101], v[66:81]
	s_waitcnt lgkmcnt(0)
	v_mfma_f32_32x32x16_bf16 v[82:97], v[102:105], v[98:101], v[82:97]
	v_and_b32_sdwa v98, v35, v169 dst_sel:DWORD dst_unused:UNUSED_PAD src0_sel:WORD_1 src1_sel:DWORD
	v_and_b32_sdwa v99, v34, v169 dst_sel:DWORD dst_unused:UNUSED_PAD src0_sel:WORD_1 src1_sel:DWORD
	v_add3_u32 v102, v34, v99, s33
	v_add3_u32 v122, v35, v98, s33
	v_and_b32_sdwa v98, v37, v169 dst_sel:DWORD dst_unused:UNUSED_PAD src0_sel:WORD_1 src1_sel:DWORD
	v_and_b32_sdwa v99, v36, v169 dst_sel:DWORD dst_unused:UNUSED_PAD src0_sel:WORD_1 src1_sel:DWORD
	v_add3_u32 v103, v36, v99, s33
	v_add3_u32 v123, v37, v98, s33
	v_and_b32_sdwa v98, v39, v169 dst_sel:DWORD dst_unused:UNUSED_PAD src0_sel:WORD_1 src1_sel:DWORD
	v_and_b32_sdwa v99, v38, v169 dst_sel:DWORD dst_unused:UNUSED_PAD src0_sel:WORD_1 src1_sel:DWORD
	v_add3_u32 v104, v38, v99, s33
	v_add3_u32 v124, v39, v98, s33
	ds_read2_b64 v[98:101], v162 offset0:16 offset1:18
	v_and_b32_sdwa v105, v41, v169 dst_sel:DWORD dst_unused:UNUSED_PAD src0_sel:WORD_1 src1_sel:DWORD
	v_and_b32_sdwa v125, v40, v169 dst_sel:DWORD dst_unused:UNUSED_PAD src0_sel:WORD_1 src1_sel:DWORD
	v_add3_u32 v125, v40, v125, s33
	v_add3_u32 v105, v41, v105, s33
	v_perm_b32 v105, v105, v125, s50
	v_perm_b32 v104, v124, v104, s50
	v_perm_b32 v103, v123, v103, s50
	v_perm_b32 v102, v122, v102, s50
	s_waitcnt lgkmcnt(0)
	s_nop 0
	v_mfma_f32_32x32x16_bf16 v[66:81], v[98:101], v[102:105], v[66:81]
	ds_read2_b64 v[98:101], v175 offset0:80 offset1:82
	ds_read2_b64 v[122:125], v162 offset0:20 offset1:22
	s_waitcnt lgkmcnt(1)
	v_mfma_f32_32x32x16_bf16 v[82:97], v[98:101], v[102:105], v[82:97]
	v_and_b32_sdwa v99, v42, v169 dst_sel:DWORD dst_unused:UNUSED_PAD src0_sel:WORD_1 src1_sel:DWORD
	v_and_b32_sdwa v100, v44, v169 dst_sel:DWORD dst_unused:UNUSED_PAD src0_sel:WORD_1 src1_sel:DWORD
	v_and_b32_sdwa v101, v46, v169 dst_sel:DWORD dst_unused:UNUSED_PAD src0_sel:WORD_1 src1_sel:DWORD
	v_and_b32_sdwa v98, v43, v169 dst_sel:DWORD dst_unused:UNUSED_PAD src0_sel:WORD_1 src1_sel:DWORD
	v_add3_u32 v102, v42, v99, s33
	v_and_b32_sdwa v99, v45, v169 dst_sel:DWORD dst_unused:UNUSED_PAD src0_sel:WORD_1 src1_sel:DWORD
	v_add3_u32 v103, v44, v100, s33
	v_and_b32_sdwa v100, v47, v169 dst_sel:DWORD dst_unused:UNUSED_PAD src0_sel:WORD_1 src1_sel:DWORD
	v_add3_u32 v104, v46, v101, s33
	v_and_b32_sdwa v101, v49, v169 dst_sel:DWORD dst_unused:UNUSED_PAD src0_sel:WORD_1 src1_sel:DWORD
	v_and_b32_sdwa v105, v48, v169 dst_sel:DWORD dst_unused:UNUSED_PAD src0_sel:WORD_1 src1_sel:DWORD
	v_add3_u32 v98, v43, v98, s33
	v_add3_u32 v99, v45, v99, s33
	v_add3_u32 v100, v47, v100, s33
	v_add3_u32 v105, v48, v105, s33
	v_add3_u32 v101, v49, v101, s33
	v_perm_b32 v101, v101, v105, s50
	v_perm_b32 v100, v100, v104, s50
	v_perm_b32 v99, v99, v103, s50
	v_perm_b32 v98, v98, v102, s50
	ds_read2_b64 v[102:105], v175 offset0:84 offset1:86
	s_waitcnt lgkmcnt(1)
	v_mfma_f32_32x32x16_bf16 v[66:81], v[122:125], v[98:101], v[66:81]
	s_waitcnt lgkmcnt(0)
	v_mfma_f32_32x32x16_bf16 v[82:97], v[102:105], v[98:101], v[82:97]
	v_and_b32_sdwa v98, v51, v169 dst_sel:DWORD dst_unused:UNUSED_PAD src0_sel:WORD_1 src1_sel:DWORD
	v_and_b32_sdwa v99, v50, v169 dst_sel:DWORD dst_unused:UNUSED_PAD src0_sel:WORD_1 src1_sel:DWORD
	v_add3_u32 v102, v50, v99, s33
	v_add3_u32 v122, v51, v98, s33
	v_and_b32_sdwa v98, v53, v169 dst_sel:DWORD dst_unused:UNUSED_PAD src0_sel:WORD_1 src1_sel:DWORD
	v_and_b32_sdwa v99, v52, v169 dst_sel:DWORD dst_unused:UNUSED_PAD src0_sel:WORD_1 src1_sel:DWORD
	v_add3_u32 v103, v52, v99, s33
	v_add3_u32 v123, v53, v98, s33
	v_and_b32_sdwa v98, v55, v169 dst_sel:DWORD dst_unused:UNUSED_PAD src0_sel:WORD_1 src1_sel:DWORD
	v_and_b32_sdwa v99, v54, v169 dst_sel:DWORD dst_unused:UNUSED_PAD src0_sel:WORD_1 src1_sel:DWORD
	v_add3_u32 v104, v54, v99, s33
	v_add3_u32 v124, v55, v98, s33
	ds_read2_b64 v[98:101], v162 offset0:24 offset1:26
	v_and_b32_sdwa v105, v57, v169 dst_sel:DWORD dst_unused:UNUSED_PAD src0_sel:WORD_1 src1_sel:DWORD
	v_and_b32_sdwa v125, v56, v169 dst_sel:DWORD dst_unused:UNUSED_PAD src0_sel:WORD_1 src1_sel:DWORD
	v_add3_u32 v125, v56, v125, s33
	v_add3_u32 v105, v57, v105, s33
	v_perm_b32 v105, v105, v125, s50
	v_perm_b32 v104, v124, v104, s50
	v_perm_b32 v103, v123, v103, s50
	v_perm_b32 v102, v122, v102, s50
	s_waitcnt lgkmcnt(0)
	s_nop 0
	v_mfma_f32_32x32x16_bf16 v[66:81], v[98:101], v[102:105], v[66:81]
	ds_read2_b64 v[122:125], v175 offset0:88 offset1:90
	ds_read2_b64 v[98:101], v162 offset0:28 offset1:30
	s_waitcnt lgkmcnt(1)
	v_mfma_f32_32x32x16_bf16 v[82:97], v[122:125], v[102:105], v[82:97]
	v_and_b32_sdwa v102, v59, v169 dst_sel:DWORD dst_unused:UNUSED_PAD src0_sel:WORD_1 src1_sel:DWORD
	v_and_b32_sdwa v103, v58, v169 dst_sel:DWORD dst_unused:UNUSED_PAD src0_sel:WORD_1 src1_sel:DWORD
	v_add3_u32 v122, v58, v103, s33
	v_add3_u32 v176, v59, v102, s33
	v_and_b32_sdwa v102, v61, v169 dst_sel:DWORD dst_unused:UNUSED_PAD src0_sel:WORD_1 src1_sel:DWORD
	v_and_b32_sdwa v103, v60, v169 dst_sel:DWORD dst_unused:UNUSED_PAD src0_sel:WORD_1 src1_sel:DWORD
	v_add3_u32 v123, v60, v103, s33
	v_add3_u32 v177, v61, v102, s33
	v_and_b32_sdwa v102, v63, v169 dst_sel:DWORD dst_unused:UNUSED_PAD src0_sel:WORD_1 src1_sel:DWORD
	v_and_b32_sdwa v103, v62, v169 dst_sel:DWORD dst_unused:UNUSED_PAD src0_sel:WORD_1 src1_sel:DWORD
	v_add3_u32 v124, v62, v103, s33
	v_add3_u32 v178, v63, v102, s33
	v_and_b32_sdwa v102, v65, v169 dst_sel:DWORD dst_unused:UNUSED_PAD src0_sel:WORD_1 src1_sel:DWORD
	v_and_b32_sdwa v103, v64, v169 dst_sel:DWORD dst_unused:UNUSED_PAD src0_sel:WORD_1 src1_sel:DWORD
	v_add3_u32 v125, v64, v103, s33
	v_add3_u32 v179, v65, v102, s33
	ds_read2_b64 v[102:105], v175 offset0:92 offset1:94
	v_perm_b32 v125, v179, v125, s50
	v_perm_b32 v124, v178, v124, s50
	v_perm_b32 v123, v177, v123, s50
	v_perm_b32 v122, v176, v122, s50
	ds_read_b128 v[176:179], v163 offset:34816
	ds_read_b128 v[180:183], v163 offset:34848
	ds_read_b128 v[184:187], v174 offset:53248
	ds_read_b128 v[188:191], v174 offset:53280
	s_waitcnt lgkmcnt(1)
	v_mfma_f32_32x32x16_bf16 v[2:17], v[176:179], v[184:187], v[2:17]
	s_waitcnt lgkmcnt(0)
	v_mfma_f32_32x32x16_bf16 v[2:17], v[180:183], v[188:191], v[2:17]
	ds_read_b128 v[176:179], v163 offset:34880
	ds_read_b128 v[180:183], v174 offset:53312
	s_waitcnt lgkmcnt(0)
	v_mfma_f32_32x32x16_bf16 v[2:17], v[176:179], v[180:183], v[2:17]
	ds_read_b128 v[176:179], v163 offset:34912
	ds_read_b128 v[180:183], v174 offset:53344
	s_waitcnt lgkmcnt(0)
	v_mfma_f32_32x32x16_bf16 v[2:17], v[176:179], v[180:183], v[2:17]
	ds_read_b128 v[176:179], v155
	ds_read_b128 v[180:183], v155 offset:32
	s_waitcnt lgkmcnt(1)
	s_nop 8
	v_pk_mul_f32 v[2:3], v[176:177], v[2:3]
	v_pk_mul_f32 v[4:5], v[4:5], v[178:179]
	ds_read_b128 v[176:179], v155 offset:64
	s_waitcnt lgkmcnt(1)
	v_pk_mul_f32 v[6:7], v[6:7], v[180:181]
	v_pk_mul_f32 v[8:9], v[8:9], v[182:183]
	s_waitcnt lgkmcnt(0)
	v_pk_mul_f32 v[10:11], v[10:11], v[176:177]
	v_pk_mul_f32 v[12:13], v[12:13], v[178:179]
	ds_read_b128 v[176:179], v155 offset:96
	s_waitcnt lgkmcnt(0)
	v_pk_mul_f32 v[14:15], v[14:15], v[176:177]
	v_pk_mul_f32 v[16:17], v[16:17], v[178:179]
	ds_read_b128 v[176:179], v163 offset:39424
	ds_read_b128 v[180:183], v163 offset:39456
	ds_read_b128 v[184:187], v174 offset:53248
	ds_read_b128 v[188:191], v174 offset:53280
	s_waitcnt lgkmcnt(1)
	v_mfma_f32_32x32x16_bf16 v[18:33], v[176:179], v[184:187], v[18:33]
	s_waitcnt lgkmcnt(0)
	v_mfma_f32_32x32x16_bf16 v[18:33], v[180:183], v[188:191], v[18:33]
	ds_read_b128 v[176:179], v163 offset:39488
	ds_read_b128 v[180:183], v174 offset:53312
	s_waitcnt lgkmcnt(0)
	v_mfma_f32_32x32x16_bf16 v[18:33], v[176:179], v[180:183], v[18:33]
	ds_read_b128 v[176:179], v163 offset:39520
	ds_read_b128 v[180:183], v174 offset:53344
	s_waitcnt lgkmcnt(0)
	v_mfma_f32_32x32x16_bf16 v[18:33], v[176:179], v[180:183], v[18:33]
	ds_read_b128 v[176:179], v155 offset:128
	ds_read_b128 v[180:183], v155 offset:160
	s_waitcnt lgkmcnt(1)
	s_nop 8
	v_pk_mul_f32 v[18:19], v[176:177], v[18:19]
	v_pk_mul_f32 v[20:21], v[20:21], v[178:179]
	ds_read_b128 v[176:179], v155 offset:192
	s_waitcnt lgkmcnt(1)
	v_pk_mul_f32 v[22:23], v[22:23], v[180:181]
	v_pk_mul_f32 v[24:25], v[24:25], v[182:183]
	s_waitcnt lgkmcnt(0)
	v_pk_mul_f32 v[26:27], v[26:27], v[176:177]
	v_pk_mul_f32 v[28:29], v[28:29], v[178:179]
	ds_read_b128 v[176:179], v155 offset:224
	s_waitcnt lgkmcnt(0)
	v_pk_mul_f32 v[30:31], v[30:31], v[176:177]
	v_pk_mul_f32 v[32:33], v[32:33], v[178:179]
	ds_read_b128 v[176:179], v163 offset:44032
	ds_read_b128 v[180:183], v163 offset:44064
	ds_read_b128 v[184:187], v174 offset:53248
	ds_read_b128 v[188:191], v174 offset:53280
	s_waitcnt lgkmcnt(1)
	v_mfma_f32_32x32x16_bf16 v[34:49], v[176:179], v[184:187], v[34:49]
	s_waitcnt lgkmcnt(0)
	v_mfma_f32_32x32x16_bf16 v[34:49], v[180:183], v[188:191], v[34:49]
	ds_read_b128 v[176:179], v163 offset:44096
	ds_read_b128 v[180:183], v174 offset:53312
	s_waitcnt lgkmcnt(0)
	v_mfma_f32_32x32x16_bf16 v[34:49], v[176:179], v[180:183], v[34:49]
	ds_read_b128 v[176:179], v163 offset:44128
	ds_read_b128 v[180:183], v174 offset:53344
	s_waitcnt lgkmcnt(0)
	v_mfma_f32_32x32x16_bf16 v[34:49], v[176:179], v[180:183], v[34:49]
	ds_read_b128 v[176:179], v155 offset:256
	ds_read_b128 v[180:183], v155 offset:288
	s_waitcnt lgkmcnt(1)
	s_nop 8
	v_pk_mul_f32 v[34:35], v[176:177], v[34:35]
	v_pk_mul_f32 v[36:37], v[36:37], v[178:179]
	ds_read_b128 v[176:179], v155 offset:320
	s_waitcnt lgkmcnt(1)
	v_pk_mul_f32 v[38:39], v[38:39], v[180:181]
	v_pk_mul_f32 v[40:41], v[40:41], v[182:183]
	s_waitcnt lgkmcnt(0)
	v_pk_mul_f32 v[42:43], v[42:43], v[176:177]
	v_pk_mul_f32 v[44:45], v[44:45], v[178:179]
	ds_read_b128 v[176:179], v155 offset:352
	s_waitcnt lgkmcnt(0)
	v_pk_mul_f32 v[46:47], v[46:47], v[176:177]
	v_pk_mul_f32 v[48:49], v[48:49], v[178:179]
	ds_read_b128 v[176:179], v163 offset:48640
	ds_read_b128 v[180:183], v163 offset:48672
	ds_read_b128 v[184:187], v174 offset:53248
	ds_read_b128 v[188:191], v174 offset:53280
	s_waitcnt lgkmcnt(1)
	v_mfma_f32_32x32x16_bf16 v[50:65], v[176:179], v[184:187], v[50:65]
	s_waitcnt lgkmcnt(0)
	v_mfma_f32_32x32x16_bf16 v[50:65], v[180:183], v[188:191], v[50:65]
	ds_read_b128 v[176:179], v163 offset:48704
	ds_read_b128 v[180:183], v174 offset:53312
	s_waitcnt lgkmcnt(0)
	v_mfma_f32_32x32x16_bf16 v[50:65], v[176:179], v[180:183], v[50:65]
	ds_read_b128 v[176:179], v163 offset:48736
	ds_read_b128 v[180:183], v174 offset:53344
	s_waitcnt lgkmcnt(0)
	v_mfma_f32_32x32x16_bf16 v[50:65], v[176:179], v[180:183], v[50:65]
	ds_read_b128 v[176:179], v155 offset:384
	ds_read_b128 v[180:183], v155 offset:416
	s_waitcnt lgkmcnt(1)
	s_nop 8
	v_pk_mul_f32 v[50:51], v[176:177], v[50:51]
	v_pk_mul_f32 v[52:53], v[52:53], v[178:179]
	ds_read_b128 v[176:179], v155 offset:448
	s_waitcnt lgkmcnt(1)
	v_pk_mul_f32 v[54:55], v[54:55], v[180:181]
	v_pk_mul_f32 v[56:57], v[56:57], v[182:183]
	s_waitcnt lgkmcnt(0)
	v_pk_mul_f32 v[58:59], v[58:59], v[176:177]
	v_pk_mul_f32 v[60:61], v[60:61], v[178:179]
	ds_read_b128 v[176:179], v155 offset:480
	s_waitcnt lgkmcnt(0)
	v_pk_mul_f32 v[62:63], v[62:63], v[176:177]
	v_pk_mul_f32 v[64:65], v[64:65], v[178:179]
	v_mfma_f32_32x32x16_bf16 v[66:81], v[98:101], v[122:125], v[66:81]
	s_barrier
	v_add_u32_e32 v98, 0x4200, v171
	s_waitcnt vmcnt(3)
	v_and_b32_e32 v177, 0xffff0000, v121
	v_and_b32_e32 v176, 0xffff0000, v120
	s_mov_b32 s42, 0x800000
	v_mfma_f32_32x32x16_bf16 v[82:97], v[102:105], v[122:125], v[82:97]
	s_nop 4
	ds_write2_b32 v171, v66, v67 offset1:132
	v_add_u32_e32 v66, 0x400, v171
	ds_write2_b32 v66, v68, v69 offset0:8 offset1:140
	v_add_u32_e32 v66, 0x4600, v171
	v_lshlrev_b32_e32 v105, 16, v119
	v_lshlrev_b32_e32 v104, 16, v118
	v_and_b32_e32 v123, 0xffff0000, v119
	ds_write2_b32 v66, v84, v85 offset0:8 offset1:140
	v_add_u32_e32 v66, 0x1000, v171
	ds_write2_b32 v66, v70, v71 offset0:32 offset1:164
	v_add_u32_e32 v66, 0x5200, v171
	ds_write2_b32 v66, v86, v87 offset0:32 offset1:164
	v_add_u32_e32 v66, 0x1400, v171
	ds_write2_b32 v66, v72, v73 offset0:40 offset1:172
	v_add_u32_e32 v66, 0x5600, v171
	ds_write2_b32 v66, v88, v89 offset0:40 offset1:172
	v_add_u32_e32 v66, 0x2000, v171
	ds_write2_b32 v66, v74, v75 offset0:64 offset1:196
	v_add_u32_e32 v66, 0x6200, v171
	ds_write2_b32 v66, v90, v91 offset0:64 offset1:196
	v_add_u32_e32 v66, 0x2400, v171
	ds_write2_b32 v66, v76, v77 offset0:72 offset1:204
	v_add_u32_e32 v66, 0x6600, v171
	ds_write2_b32 v66, v92, v93 offset0:72 offset1:204
	v_add_u32_e32 v66, 0x3000, v171
	ds_write2_b32 v66, v78, v79 offset0:96 offset1:228
	v_add_u32_e32 v66, 0x7200, v171
	ds_write2_b32 v66, v94, v95 offset0:96 offset1:228
	v_add_u32_e32 v66, 0x3400, v171
	ds_write2_b32 v66, v80, v81 offset0:104 offset1:236
	v_add_u32_e32 v66, 0x7600, v171
	ds_write2_b32 v98, v82, v83 offset1:132
	ds_write2_b32 v66, v96, v97 offset0:104 offset1:236
	s_waitcnt lgkmcnt(0)
	s_barrier
	global_load_dwordx4 v[92:95], v[128:129], off
	global_load_dwordx4 v[96:99], v[128:129], off offset:16
	ds_read_b128 v[100:103], v157
	v_and_b32_e32 v122, 0xffff0000, v118
	v_lshlrev_b32_e32 v125, 16, v121
	v_lshlrev_b32_e32 v124, 16, v120
	ds_read_b128 v[118:121], v157 offset:16
	ds_read_b128 v[78:81], v157 offset:32
	ds_read_b128 v[74:77], v157 offset:48
	s_waitcnt lgkmcnt(3)
	v_pk_mul_f32 v[182:183], v[100:101], v[100:101]
	v_mov_b32_e32 v178, v100
	v_pk_mul_f32 v[180:181], v[102:103], v[102:103]
	v_add_f32_e32 v100, v182, v183
	v_add_f32_e32 v100, v100, v180
	s_waitcnt lgkmcnt(2)
	v_pk_mul_f32 v[186:187], v[118:119], v[118:119]
	v_add_f32_e32 v100, v100, v181
	v_add_f32_e32 v100, v100, v186
	v_pk_mul_f32 v[184:185], v[120:121], v[120:121]
	v_add_f32_e32 v100, v100, v187
	v_add_f32_e32 v100, v100, v184
	s_waitcnt lgkmcnt(1)
	v_pk_mul_f32 v[190:191], v[78:79], v[78:79]
	v_add_f32_e32 v100, v100, v185
	v_add_f32_e32 v100, v100, v190
	v_pk_mul_f32 v[188:189], v[80:81], v[80:81]
	v_add_f32_e32 v100, v100, v191
	ds_read_b128 v[86:89], v157 offset:64
	ds_read_b128 v[82:85], v157 offset:80
	v_add_f32_e32 v100, v100, v188
	s_waitcnt lgkmcnt(2)
	v_pk_mul_f32 v[194:195], v[74:75], v[74:75]
	v_add_f32_e32 v100, v100, v189
	v_add_f32_e32 v100, v100, v194
	v_pk_mul_f32 v[192:193], v[76:77], v[76:77]
	v_add_f32_e32 v100, v100, v195
	v_add_f32_e32 v100, v100, v192
	s_waitcnt lgkmcnt(1)
	v_pk_mul_f32 v[198:199], v[86:87], v[86:87]
	v_add_f32_e32 v100, v100, v193
	v_add_f32_e32 v100, v100, v198
	v_pk_mul_f32 v[196:197], v[88:89], v[88:89]
	v_add_f32_e32 v100, v100, v199
	ds_read_b128 v[66:69], v157 offset:96
	ds_read_b128 v[70:73], v157 offset:112
	v_add_f32_e32 v100, v100, v196
	s_waitcnt lgkmcnt(2)
	v_pk_mul_f32 v[202:203], v[82:83], v[82:83]
	v_add_f32_e32 v100, v100, v197
	v_add_f32_e32 v100, v100, v202
	v_pk_mul_f32 v[200:201], v[84:85], v[84:85]
	v_add_f32_e32 v100, v100, v203
	v_add_f32_e32 v100, v100, v200
	s_waitcnt lgkmcnt(1)
	v_pk_mul_f32 v[204:205], v[66:67], v[66:67]
	v_add_f32_e32 v100, v100, v201
	v_add_f32_e32 v100, v100, v204
	v_pk_mul_f32 v[206:207], v[68:69], v[68:69]
	v_add_f32_e32 v100, v100, v205
	v_add_f32_e32 v100, v100, v206
	s_waitcnt lgkmcnt(0)
	v_pk_mul_f32 v[208:209], v[70:71], v[70:71]
	v_add_f32_e32 v100, v100, v207
	v_add_f32_e32 v100, v100, v208
	v_pk_mul_f32 v[210:211], v[72:73], v[72:73]
	v_add_f32_e32 v100, v100, v209
	v_add_f32_e32 v100, v100, v210
	v_add_f32_e32 v175, v100, v211
	ds_bpermute_b32 v180, v172, v175
	v_mov_b32_e32 v179, v102
	v_mov_b32_e32 v102, v101
	v_mov_b32_e32 v181, v120
	v_mov_b32_e32 v120, v119
	v_lshl_add_u64 v[90:91], s[82:83], 0, v[144:145]
	s_add_i32 s44, s44, -1
	v_lshl_add_u64 v[138:139], v[138:139], 0, s[62:63]
	v_lshl_add_u64 v[140:141], v[140:141], 0, s[90:91]
	v_lshl_add_u64 v[142:143], v[142:143], 0, s[62:63]
	s_cmp_eq_u32 s44, 0
	v_lshl_add_u64 v[144:145], v[144:145], 0, s[90:91]
	s_waitcnt vmcnt(1)
	v_mov_b32_e32 v100, v92
	s_waitcnt lgkmcnt(0)
	v_add_f32_e32 v92, v175, v180
	ds_bpermute_b32 v175, v173, v92
	v_mov_b32_e32 v101, v94
	v_mov_b32_e32 v94, v93
	v_mov_b32_e32 v180, v118
	s_waitcnt vmcnt(0)
	v_mov_b32_e32 v118, v96
	s_waitcnt lgkmcnt(0)
	v_add_f32_e32 v92, v92, v175
	v_fmamk_f32 v92, v92, 0x3c000000, v164
	v_mul_f32_e32 v93, 0x4b800000, v92
	v_cmp_gt_f32_e32 vcc, s42, v92
	v_mov_b32_e32 v119, v98
	v_mov_b32_e32 v98, v97
	v_cndmask_b32_e32 v92, v92, v93, vcc
	v_rsq_f32_e32 v92, v92
	s_nop 0
	v_mul_f32_e32 v93, 0x45800000, v92
	v_cndmask_b32_e32 v92, v92, v93, vcc
	v_pk_mul_f32 v[96:97], v[178:179], v[92:93] op_sel_hi:[1,0]
	s_nop 0
	v_pk_mul_f32 v[96:97], v[100:101], v[96:97]
	v_pk_mul_f32 v[100:101], v[102:103], v[92:93] op_sel_hi:[1,0]
	v_pk_mul_f32 v[96:97], v[96:97], v[104:105]
	v_pk_mul_f32 v[94:95], v[94:95], v[100:101]
	v_and_b32_sdwa v100, v96, v169 dst_sel:DWORD dst_unused:UNUSED_PAD src0_sel:WORD_1 src1_sel:DWORD
	v_pk_mul_f32 v[94:95], v[94:95], v[122:123]
	v_add3_u32 v96, v96, v100, s33
	v_and_b32_sdwa v100, v94, v169 dst_sel:DWORD dst_unused:UNUSED_PAD src0_sel:WORD_1 src1_sel:DWORD
	v_and_b32_sdwa v93, v97, v169 dst_sel:DWORD dst_unused:UNUSED_PAD src0_sel:WORD_1 src1_sel:DWORD
	v_add3_u32 v94, v94, v100, s33
	v_add3_u32 v93, v97, v93, s33
	v_and_b32_sdwa v97, v95, v169 dst_sel:DWORD dst_unused:UNUSED_PAD src0_sel:WORD_1 src1_sel:DWORD
	v_and_b32_e32 v94, 0xffff0000, v94
	v_add3_u32 v95, v95, v97, s33
	v_or_b32_sdwa v94, v94, v96 dst_sel:DWORD dst_unused:UNUSED_PAD src0_sel:DWORD src1_sel:WORD_1
	v_pk_mul_f32 v[96:97], v[180:181], v[92:93] op_sel_hi:[1,0]
	v_pk_mul_f32 v[100:101], v[120:121], v[92:93] op_sel_hi:[1,0]
	v_pk_mul_f32 v[96:97], v[118:119], v[96:97]
	v_and_b32_e32 v95, 0xffff0000, v95
	v_pk_mul_f32 v[96:97], v[96:97], v[124:125]
	v_pk_mul_f32 v[98:99], v[98:99], v[100:101]
	v_or_b32_sdwa v95, v95, v93 dst_sel:DWORD dst_unused:UNUSED_PAD src0_sel:DWORD src1_sel:WORD_1
	v_pk_mul_f32 v[98:99], v[98:99], v[176:177]
	v_and_b32_sdwa v93, v97, v169 dst_sel:DWORD dst_unused:UNUSED_PAD src0_sel:WORD_1 src1_sel:DWORD
	v_and_b32_sdwa v100, v96, v169 dst_sel:DWORD dst_unused:UNUSED_PAD src0_sel:WORD_1 src1_sel:DWORD
	v_add3_u32 v96, v96, v100, s33
	v_add3_u32 v93, v97, v93, s33
	v_and_b32_sdwa v97, v99, v169 dst_sel:DWORD dst_unused:UNUSED_PAD src0_sel:WORD_1 src1_sel:DWORD
	v_and_b32_sdwa v100, v98, v169 dst_sel:DWORD dst_unused:UNUSED_PAD src0_sel:WORD_1 src1_sel:DWORD
	v_add3_u32 v97, v99, v97, s33
	v_add3_u32 v98, v98, v100, s33
	v_and_b32_e32 v97, 0xffff0000, v97
	v_and_b32_e32 v98, 0xffff0000, v98
	v_or_b32_sdwa v97, v97, v93 dst_sel:DWORD dst_unused:UNUSED_PAD src0_sel:DWORD src1_sel:WORD_1
	v_or_b32_sdwa v96, v98, v96 dst_sel:DWORD dst_unused:UNUSED_PAD src0_sel:DWORD src1_sel:WORD_1
	global_store_dwordx4 v[90:91], v[94:97], off offset:-32
	global_load_dwordx4 v[94:97], v[128:129], off offset:32
	s_nop 0
	global_load_dwordx4 v[98:101], v[128:129], off offset:48
	v_mov_b32_e32 v118, v78
	v_mov_b32_e32 v119, v80
	v_mov_b32_e32 v80, v79
	v_mov_b32_e32 v78, v74
	v_mov_b32_e32 v79, v76
	v_mov_b32_e32 v76, v75
	v_pk_mul_f32 v[74:75], v[118:119], v[92:93] op_sel_hi:[1,0]
	v_lshlrev_b32_e32 v103, 16, v115
	v_lshlrev_b32_e32 v102, 16, v114
	v_pk_mul_f32 v[80:81], v[80:81], v[92:93] op_sel_hi:[1,0]
	v_and_b32_e32 v105, 0xffff0000, v115
	v_and_b32_e32 v104, 0xffff0000, v114
	v_lshlrev_b32_e32 v115, 16, v117
	v_lshlrev_b32_e32 v114, 16, v116
	v_and_b32_e32 v117, 0xffff0000, v117
	v_and_b32_e32 v116, 0xffff0000, v116
	s_waitcnt vmcnt(1)
	v_mov_b32_e32 v118, v94
	v_mov_b32_e32 v119, v96
	v_pk_mul_f32 v[74:75], v[74:75], v[118:119]
	v_mov_b32_e32 v96, v95
	v_pk_mul_f32 v[74:75], v[74:75], v[102:103]
	v_pk_mul_f32 v[80:81], v[80:81], v[96:97]
	v_and_b32_sdwa v93, v75, v169 dst_sel:DWORD dst_unused:UNUSED_PAD src0_sel:WORD_1 src1_sel:DWORD
	v_pk_mul_f32 v[80:81], v[80:81], v[104:105]
	v_and_b32_sdwa v94, v74, v169 dst_sel:DWORD dst_unused:UNUSED_PAD src0_sel:WORD_1 src1_sel:DWORD
	v_add3_u32 v74, v74, v94, s33
	v_add3_u32 v75, v75, v93, s33
	v_and_b32_sdwa v93, v81, v169 dst_sel:DWORD dst_unused:UNUSED_PAD src0_sel:WORD_1 src1_sel:DWORD
	v_and_b32_sdwa v94, v80, v169 dst_sel:DWORD dst_unused:UNUSED_PAD src0_sel:WORD_1 src1_sel:DWORD
	v_add3_u32 v81, v81, v93, s33
	v_add3_u32 v80, v80, v94, s33
	v_and_b32_e32 v81, 0xffff0000, v81
	v_and_b32_e32 v80, 0xffff0000, v80
	v_or_b32_sdwa v75, v81, v75 dst_sel:DWORD dst_unused:UNUSED_PAD src0_sel:DWORD src1_sel:WORD_1
	v_or_b32_sdwa v74, v80, v74 dst_sel:DWORD dst_unused:UNUSED_PAD src0_sel:DWORD src1_sel:WORD_1
	v_pk_mul_f32 v[78:79], v[78:79], v[92:93] op_sel_hi:[1,0]
	s_waitcnt vmcnt(0)
	v_mov_b32_e32 v80, v98
	v_mov_b32_e32 v81, v100
	v_pk_mul_f32 v[78:79], v[78:79], v[80:81]
	v_pk_mul_f32 v[76:77], v[76:77], v[92:93] op_sel_hi:[1,0]
	v_mov_b32_e32 v100, v99
	v_pk_mul_f32 v[78:79], v[78:79], v[114:115]
	v_pk_mul_f32 v[76:77], v[76:77], v[100:101]
	v_and_b32_sdwa v80, v79, v169 dst_sel:DWORD dst_unused:UNUSED_PAD src0_sel:WORD_1 src1_sel:DWORD
	v_pk_mul_f32 v[76:77], v[76:77], v[116:117]
	v_and_b32_sdwa v81, v78, v169 dst_sel:DWORD dst_unused:UNUSED_PAD src0_sel:WORD_1 src1_sel:DWORD
	v_add3_u32 v78, v78, v81, s33
	v_add3_u32 v79, v79, v80, s33
	v_and_b32_sdwa v80, v77, v169 dst_sel:DWORD dst_unused:UNUSED_PAD src0_sel:WORD_1 src1_sel:DWORD
	v_and_b32_sdwa v81, v76, v169 dst_sel:DWORD dst_unused:UNUSED_PAD src0_sel:WORD_1 src1_sel:DWORD
	v_add3_u32 v77, v77, v80, s33
	v_add3_u32 v76, v76, v81, s33
	v_and_b32_e32 v77, 0xffff0000, v77
	v_and_b32_e32 v76, 0xffff0000, v76
	v_or_b32_sdwa v77, v77, v79 dst_sel:DWORD dst_unused:UNUSED_PAD src0_sel:DWORD src1_sel:WORD_1
	v_or_b32_sdwa v76, v76, v78 dst_sel:DWORD dst_unused:UNUSED_PAD src0_sel:DWORD src1_sel:WORD_1
	global_store_dwordx4 v[90:91], v[74:77], off offset:-16
	s_nop 1
	v_mov_b64_e32 v[74:75], v[236:237]
	v_mov_b64_e32 v[76:77], v[238:239]
	s_nop 0
	s_nop 1
	v_mov_b64_e32 v[78:79], v[240:241]
	v_mov_b64_e32 v[80:81], v[242:243]
	v_mov_b32_e32 v102, v86
	v_mov_b32_e32 v103, v88
	v_mov_b32_e32 v88, v87
	v_mov_b32_e32 v86, v82
	v_mov_b32_e32 v87, v84
	v_mov_b32_e32 v84, v83
	v_pk_mul_f32 v[82:83], v[102:103], v[92:93] op_sel_hi:[1,0]
	v_pk_mul_f32 v[88:89], v[88:89], v[92:93] op_sel_hi:[1,0]
	v_lshlrev_b32_e32 v95, 16, v111
	v_lshlrev_b32_e32 v94, 16, v110
	v_and_b32_e32 v97, 0xffff0000, v111
	v_and_b32_e32 v96, 0xffff0000, v110
	v_pk_mul_f32 v[86:87], v[86:87], v[92:93] op_sel_hi:[1,0]
	v_lshlrev_b32_e32 v99, 16, v113
	v_lshlrev_b32_e32 v98, 16, v112
	v_pk_mul_f32 v[84:85], v[84:85], v[92:93] op_sel_hi:[1,0]
	v_and_b32_e32 v101, 0xffff0000, v113
	v_and_b32_e32 v100, 0xffff0000, v112
	v_mov_b32_e32 v102, v74
	v_mov_b32_e32 v103, v76
	v_mov_b32_e32 v76, v75
	v_mov_b32_e32 v74, v78
	v_mov_b32_e32 v75, v80
	v_mov_b32_e32 v80, v79
	v_pk_mul_f32 v[78:79], v[82:83], v[102:103]
	v_pk_mul_f32 v[76:77], v[88:89], v[76:77]
	v_pk_mul_f32 v[74:75], v[86:87], v[74:75]
	v_pk_mul_f32 v[78:79], v[78:79], v[94:95]
	v_pk_mul_f32 v[76:77], v[76:77], v[96:97]
	v_pk_mul_f32 v[80:81], v[84:85], v[80:81]
	v_pk_mul_f32 v[82:83], v[74:75], v[98:99]
	v_and_b32_sdwa v75, v78, v169 dst_sel:DWORD dst_unused:UNUSED_PAD src0_sel:WORD_1 src1_sel:DWORD
	v_and_b32_sdwa v84, v77, v169 dst_sel:DWORD dst_unused:UNUSED_PAD src0_sel:WORD_1 src1_sel:DWORD
	v_and_b32_sdwa v85, v76, v169 dst_sel:DWORD dst_unused:UNUSED_PAD src0_sel:WORD_1 src1_sel:DWORD
	v_and_b32_sdwa v74, v79, v169 dst_sel:DWORD dst_unused:UNUSED_PAD src0_sel:WORD_1 src1_sel:DWORD
	v_add3_u32 v78, v78, v75, s33
	v_add3_u32 v75, v77, v84, s33
	v_add3_u32 v76, v76, v85, s33
	v_pk_mul_f32 v[80:81], v[80:81], v[100:101]
	v_add3_u32 v74, v79, v74, s33
	v_and_b32_e32 v75, 0xffff0000, v75
	v_and_b32_e32 v76, 0xffff0000, v76
	v_or_b32_sdwa v75, v75, v74 dst_sel:DWORD dst_unused:UNUSED_PAD src0_sel:DWORD src1_sel:WORD_1
	v_or_b32_sdwa v74, v76, v78 dst_sel:DWORD dst_unused:UNUSED_PAD src0_sel:DWORD src1_sel:WORD_1
	v_and_b32_sdwa v78, v81, v169 dst_sel:DWORD dst_unused:UNUSED_PAD src0_sel:WORD_1 src1_sel:DWORD
	v_and_b32_sdwa v79, v80, v169 dst_sel:DWORD dst_unused:UNUSED_PAD src0_sel:WORD_1 src1_sel:DWORD
	v_and_b32_sdwa v86, v83, v169 dst_sel:DWORD dst_unused:UNUSED_PAD src0_sel:WORD_1 src1_sel:DWORD
	v_and_b32_sdwa v76, v82, v169 dst_sel:DWORD dst_unused:UNUSED_PAD src0_sel:WORD_1 src1_sel:DWORD
	v_add3_u32 v78, v81, v78, s33
	v_add3_u32 v79, v80, v79, s33
	v_add3_u32 v76, v82, v76, s33
	v_add3_u32 v77, v83, v86, s33
	v_and_b32_e32 v78, 0xffff0000, v78
	v_and_b32_e32 v79, 0xffff0000, v79
	v_or_b32_sdwa v77, v78, v77 dst_sel:DWORD dst_unused:UNUSED_PAD src0_sel:DWORD src1_sel:WORD_1
	v_or_b32_sdwa v76, v79, v76 dst_sel:DWORD dst_unused:UNUSED_PAD src0_sel:DWORD src1_sel:WORD_1
	global_store_dwordx4 v[90:91], v[74:77], off
	s_nop 1
	v_mov_b64_e32 v[74:75], v[244:245]
	v_mov_b64_e32 v[76:77], v[246:247]
	s_nop 0
	s_nop 1
	v_mov_b64_e32 v[78:79], v[248:249]
	v_mov_b64_e32 v[80:81], v[250:251]
	v_mov_b32_e32 v94, v66
	v_mov_b32_e32 v95, v68
	v_mov_b32_e32 v66, v67
	v_mov_b32_e32 v67, v69
	v_mov_b32_e32 v68, v70
	v_mov_b32_e32 v69, v72
	v_mov_b32_e32 v70, v71
	v_mov_b32_e32 v71, v73
	v_pk_mul_f32 v[72:73], v[94:95], v[92:93] op_sel_hi:[1,0]
	v_pk_mul_f32 v[66:67], v[66:67], v[92:93] op_sel_hi:[1,0]
	v_pk_mul_f32 v[68:69], v[68:69], v[92:93] op_sel_hi:[1,0]
	v_pk_mul_f32 v[70:71], v[70:71], v[92:93] op_sel_hi:[1,0]
	v_and_b32_e32 v85, 0xffff0000, v107
	v_and_b32_e32 v84, 0xffff0000, v106
	v_and_b32_e32 v89, 0xffff0000, v109
	v_and_b32_e32 v88, 0xffff0000, v108
	v_lshlrev_b32_e32 v83, 16, v107
	v_lshlrev_b32_e32 v82, 16, v106
	v_lshlrev_b32_e32 v87, 16, v109
	v_lshlrev_b32_e32 v86, 16, v108
	v_mov_b32_e32 v93, v76
	v_mov_b32_e32 v76, v75
	v_mov_b32_e32 v75, v80
	v_mov_b32_e32 v80, v79
	v_mov_b32_e32 v92, v74
	v_mov_b32_e32 v74, v78
	v_pk_mul_f32 v[66:67], v[66:67], v[76:77]
	v_pk_mul_f32 v[70:71], v[70:71], v[80:81]
	v_pk_mul_f32 v[72:73], v[72:73], v[92:93]
	v_pk_mul_f32 v[68:69], v[68:69], v[74:75]
	v_pk_mul_f32 v[66:67], v[66:67], v[84:85]
	v_pk_mul_f32 v[70:71], v[70:71], v[88:89]
	v_pk_mul_f32 v[72:73], v[72:73], v[82:83]
	v_pk_mul_f32 v[68:69], v[68:69], v[86:87]
	v_and_b32_sdwa v76, v67, v169 dst_sel:DWORD dst_unused:UNUSED_PAD src0_sel:WORD_1 src1_sel:DWORD
	v_and_b32_sdwa v77, v66, v169 dst_sel:DWORD dst_unused:UNUSED_PAD src0_sel:WORD_1 src1_sel:DWORD
	v_and_b32_sdwa v80, v71, v169 dst_sel:DWORD dst_unused:UNUSED_PAD src0_sel:WORD_1 src1_sel:DWORD
	v_and_b32_sdwa v81, v70, v169 dst_sel:DWORD dst_unused:UNUSED_PAD src0_sel:WORD_1 src1_sel:DWORD
	v_and_b32_sdwa v74, v73, v169 dst_sel:DWORD dst_unused:UNUSED_PAD src0_sel:WORD_1 src1_sel:DWORD
	v_and_b32_sdwa v75, v72, v169 dst_sel:DWORD dst_unused:UNUSED_PAD src0_sel:WORD_1 src1_sel:DWORD
	v_and_b32_sdwa v78, v69, v169 dst_sel:DWORD dst_unused:UNUSED_PAD src0_sel:WORD_1 src1_sel:DWORD
	v_and_b32_sdwa v79, v68, v169 dst_sel:DWORD dst_unused:UNUSED_PAD src0_sel:WORD_1 src1_sel:DWORD
	v_add3_u32 v67, v67, v76, s33
	v_add3_u32 v66, v66, v77, s33
	v_add3_u32 v71, v71, v80, s33
	v_add3_u32 v70, v70, v81, s33
	v_add3_u32 v72, v72, v75, s33
	v_add3_u32 v73, v73, v74, s33
	v_add3_u32 v68, v68, v79, s33
	v_add3_u32 v69, v69, v78, s33
	v_and_b32_e32 v67, 0xffff0000, v67
	v_and_b32_e32 v66, 0xffff0000, v66
	v_and_b32_e32 v71, 0xffff0000, v71
	v_and_b32_e32 v70, 0xffff0000, v70
	v_or_b32_sdwa v67, v67, v73 dst_sel:DWORD dst_unused:UNUSED_PAD src0_sel:DWORD src1_sel:WORD_1
	v_or_b32_sdwa v66, v66, v72 dst_sel:DWORD dst_unused:UNUSED_PAD src0_sel:DWORD src1_sel:WORD_1
	v_or_b32_sdwa v69, v71, v69 dst_sel:DWORD dst_unused:UNUSED_PAD src0_sel:DWORD src1_sel:WORD_1
	v_or_b32_sdwa v68, v70, v68 dst_sel:DWORD dst_unused:UNUSED_PAD src0_sel:DWORD src1_sel:WORD_1
	global_store_dwordx4 v[90:91], v[66:69], off offset:16
	s_cbranch_scc1 .LBB0_167
